# GEMM P1/P4/P5/P6: first K-loop iteration peeled with C=0 in the first-touch MFMAs instead of 128 v_mov zeroing per unit (on top of the K-loop trims)
# speedup vs baseline: 1.0064x; 1.0064x over previous
; #define PG8_STAGE(bufoff, gbase, voff) do { _Pragma("unroll") for (int _i = 0; _i < 2; ++_i) \
;         __builtin_amdgcn_global_load_lds((const unsigned*)((const char*)(gbase) + (voff)[_i]), (PG8_LAS unsigned*)(lds + (bufoff) + ldsw + _i * 8192), 16, 0, 0); } while (0)
; #define PG8_LDA(dst, b, h) do { _Pragma("unroll") for (int m = 0; m < 4; ++m) _Pragma("unroll") for (int k = 0; k < 2; ++k) dst[m][k] = *(const PG8_LAS bf16x8*)(lds + PG8_SA(b, h) + aoff + m * 2048 + k * 1024); } while (0)
; #define PG8_LDB(dst, b, h) do { _Pragma("unroll") for (int n = 0; n < 2; ++n) _Pragma("unroll") for (int k = 0; k < 2; ++k) dst[n][k] = *(const PG8_LAS bf16x8*)(lds + PG8_SB(b, h) + boff + n * 2048 + k * 1024); } while (0)
; #define PG8_MMA(ai, bj, At, Bt) do { __builtin_amdgcn_s_setprio(1); _Pragma("unroll") for (int m = 0; m < 4; ++m) _Pragma("unroll") for (int n = 0; n < 2; ++n) _Pragma("unroll") for (int k = 0; k < 2; ++k) \
;         acc[ai][bj][m][n] = __builtin_amdgcn_mfma_f32_16x16x32_bf16(Bt[n][k], At[m][k], acc[ai][bj][m][n], 0, 0, 0); __builtin_amdgcn_s_setprio(0); } while (0)
; template <class Epi, class Sched, bool ALIGN_EPI = false, bool SP2 = false>
; __device__ __forceinline__ void gemm_phase(PG8_LAS unsigned char* lds, const Gemm g, const Sched& S, const Epi& E) {
;     ...
;         const char* nA = has_next ? (const char*)g.A + (size_t)nxt.pm * tstep : cA; const char* nB = has_next ? (const char*)g.Bt + (size_t)nxt.pn * tstep : cB;
;         for (int t = 0; t < nt; t += 2) {
;             if constexpr (Epi::HAS_MID) { if (t == (nt >> 1)) E.mid(acc, cur, wr, wc, fr, fq); }
;             const bool last = (t == nt - 2);
;             const char* a1 = cA + (size_t)(t + 1) * kstep;
;             const char* a2 = last ? nA : cA + (size_t)(t + 2) * kstep; const char* b2 = last ? nB : cB + (size_t)(t + 2) * kstep;
;             const char* a3 = a2 + kstep; const char* b3 = b2 + kstep;
;             if (last && has_next) S.a_ready(nxt);
;             if constexpr (SP2) {
;             PG8_LDB(B0, 0, 0); PG8_LDB(B1, 0, 1); PG8_SCHED; PG8_LDA(At, 0, 0); PG8_STAGE(PG8_SA(1, 1), a1 + hstep, voffA);
;             PG8_WAIT_V(8); PG8_WAIT_L(0); PG8_BAR; PG8_MMA(0, 0, At, B0); PG8_MMA(0, 1, At, B1); PG8_BAR; PG8_SCHED;
;             PG8_LDA(At, 0, 1); PG8_STAGE(PG8_SB(0, 0), b2, voffB); PG8_STAGE(PG8_SB(0, 1), b2 + hstepB, voffB); PG8_STAGE(PG8_SA(0, 0), a2, voffA);
.LBB0_149:
	s_ashr_i32 s17, s16, 31
	s_lshl_b64 s[18:19], s[16:17], 19
	s_add_u32 s18, s62, s18
	s_addc_u32 s19, s63, s19
	s_and_b64 s[20:21], s[4:5], exec
	s_cselect_b32 s17, s19, s25
	s_cselect_b32 s71, s18, s24
	s_ashr_i32 s15, s14, 31
	s_lshl_b64 s[20:21], s[14:15], 19
	s_add_u32 s20, s3, s20
	s_addc_u32 s21, s80, s21
	s_and_b64 s[28:29], s[4:5], exec
	s_cselect_b32 s15, s21, s27
	s_cselect_b32 s72, s20, s26
	s_add_u32 s24, s24, 0xc000
	s_addc_u32 s25, s25, 0
	s_add_u32 s73, s26, 0x10000
	s_addc_u32 s74, s27, 0
	s_mov_b32 s75, -2
	ds_read_b128 v[156:159], v150
	ds_read_b128 v[160:163], v150 offset:1024
	ds_read_b128 v[164:167], v150 offset:2048
	ds_read_b128 v[168:171], v150 offset:3072
	ds_read_b128 v[172:175], v151
	ds_read_b128 v[176:179], v151 offset:1024
	ds_read_b128 v[180:183], v151 offset:2048
	ds_read_b128 v[184:187], v151 offset:3072
	s_add_u32 s26, s24, 0x4000
	s_addc_u32 s27, s25, 0
	s_cmp_eq_u32 s75, 12
	s_cselect_b32 s40, s71, s26
	s_cselect_b32 s41, s17, s27
	s_cselect_b32 s28, s72, s73
	s_cselect_b32 s29, s15, s74
	s_add_u32 s26, s40, 0x8000
	s_addc_u32 s27, s41, 0
	s_add_i32 m0, s23, 0xc000
	ds_read_b128 v[188:191], v152
	ds_read_b128 v[192:195], v152 offset:1024
	ds_read_b128 v[196:199], v152 offset:2048
	ds_read_b128 v[200:203], v152 offset:3072
	ds_read_b128 v[204:207], v152 offset:4096
	ds_read_b128 v[208:211], v152 offset:5120
	ds_read_b128 v[212:215], v152 offset:6144
	ds_read_b128 v[220:223], v152 offset:7168
	global_load_lds_dwordx4 v140, s[24:25]
	s_add_i32 m0, s23, 0xe000
	s_nop 0
	global_load_lds_dwordx4 v142, s[24:25]
	s_waitcnt vmcnt(8)
	s_waitcnt lgkmcnt(0)
	s_setprio 1
	s_barrier
	v_mfma_f32_16x16x32_bf16 v[126:129], v[156:159], v[188:191], 0
	v_mfma_f32_16x16x32_bf16 v[122:125], v[164:167], v[188:191], 0
	v_mfma_f32_16x16x32_bf16 v[114:117], v[156:159], v[196:199], 0
	v_mfma_f32_16x16x32_bf16 v[106:109], v[164:167], v[196:199], 0
	v_mfma_f32_16x16x32_bf16 v[98:101], v[156:159], v[204:207], 0
	v_mfma_f32_16x16x32_bf16 v[90:93], v[164:167], v[204:207], 0
	v_mfma_f32_16x16x32_bf16 v[78:81], v[156:159], v[212:215], 0
	v_mfma_f32_16x16x32_bf16 v[74:77], v[164:167], v[212:215], 0
	v_mfma_f32_16x16x32_bf16 v[126:129], v[160:163], v[192:195], v[126:129]
	v_mfma_f32_16x16x32_bf16 v[122:125], v[168:171], v[192:195], v[122:125]
	v_mfma_f32_16x16x32_bf16 v[114:117], v[160:163], v[200:203], v[114:117]
	v_mfma_f32_16x16x32_bf16 v[106:109], v[168:171], v[200:203], v[106:109]
	v_mfma_f32_16x16x32_bf16 v[98:101], v[160:163], v[208:211], v[98:101]
	v_mfma_f32_16x16x32_bf16 v[90:93], v[168:171], v[208:211], v[90:93]
	v_mfma_f32_16x16x32_bf16 v[78:81], v[160:163], v[220:223], v[78:81]
	v_mfma_f32_16x16x32_bf16 v[74:77], v[168:171], v[220:223], v[74:77]
	s_setprio 0
	s_setprio 1
	v_mfma_f32_16x16x32_bf16 v[118:121], v[172:175], v[188:191], 0
	v_mfma_f32_16x16x32_bf16 v[110:113], v[180:183], v[188:191], 0
	v_mfma_f32_16x16x32_bf16 v[102:105], v[172:175], v[196:199], 0
	v_mfma_f32_16x16x32_bf16 v[94:97], v[180:183], v[196:199], 0
	v_mfma_f32_16x16x32_bf16 v[86:89], v[172:175], v[204:207], 0
	v_mfma_f32_16x16x32_bf16 v[82:85], v[180:183], v[204:207], 0
	v_mfma_f32_16x16x32_bf16 v[70:73], v[172:175], v[212:215], 0
	v_mfma_f32_16x16x32_bf16 v[66:69], v[180:183], v[212:215], 0
	v_mfma_f32_16x16x32_bf16 v[118:121], v[176:179], v[192:195], v[118:121]
	v_mfma_f32_16x16x32_bf16 v[110:113], v[184:187], v[192:195], v[110:113]
	v_mfma_f32_16x16x32_bf16 v[102:105], v[176:179], v[200:203], v[102:105]
	v_mfma_f32_16x16x32_bf16 v[94:97], v[184:187], v[200:203], v[94:97]
	v_mfma_f32_16x16x32_bf16 v[86:89], v[176:179], v[208:211], v[86:89]
	v_mfma_f32_16x16x32_bf16 v[82:85], v[184:187], v[208:211], v[82:85]
	v_mfma_f32_16x16x32_bf16 v[70:73], v[176:179], v[220:223], v[70:73]
	v_mfma_f32_16x16x32_bf16 v[66:69], v[184:187], v[220:223], v[66:69]
	s_barrier
	s_setprio 0
	s_add_i32 s76, s56, s0
	s_mov_b32 m0, s76
	ds_read_b128 v[188:191], v152 offset:16384
	ds_read_b128 v[192:195], v152 offset:17408
	ds_read_b128 v[196:199], v152 offset:18432
	ds_read_b128 v[200:203], v152 offset:19456
	ds_read_b128 v[204:207], v152 offset:20480
	ds_read_b128 v[208:211], v152 offset:21504
	ds_read_b128 v[212:215], v152 offset:22528
	ds_read_b128 v[220:223], v152 offset:23552
	global_load_lds_dwordx4 v134, s[28:29]
	s_add_i32 m0, s76, 0x2000
	s_add_u32 s76, s28, 0x1000
	s_addc_u32 s77, s29, 0
	s_add_i32 s78, s57, s0
	global_load_lds_dwordx4 v130, s[28:29]
	s_mov_b32 m0, s78
	s_nop 0
	global_load_lds_dwordx4 v134, s[76:77]
	s_add_i32 m0, s78, 0x2000
	s_nop 0
	global_load_lds_dwordx4 v130, s[76:77]
	s_mov_b32 m0, s23
	s_nop 0
	global_load_lds_dwordx4 v136, s[40:41]
	s_mov_b32 m0, s49
	s_nop 0
	global_load_lds_dwordx4 v132, s[40:41]
	s_waitcnt vmcnt(8)
	s_waitcnt lgkmcnt(0)
	s_setprio 1
	s_barrier
; #define PG8_STAGE(bufoff, gbase, voff) do { _Pragma("unroll") for (int _i = 0; _i < 2; ++_i) \
;         __builtin_amdgcn_global_load_lds((const unsigned*)((const char*)(gbase) + (voff)[_i]), (PG8_LAS unsigned*)(lds + (bufoff) + ldsw + _i * 8192), 16, 0, 0); } while (0)
; #define PG8_LDA(dst, b, h) do { _Pragma("unroll") for (int m = 0; m < 4; ++m) _Pragma("unroll") for (int k = 0; k < 2; ++k) dst[m][k] = *(const PG8_LAS bf16x8*)(lds + PG8_SA(b, h) + aoff + m * 2048 + k * 1024); } while (0)
; #define PG8_LDB(dst, b, h) do { _Pragma("unroll") for (int n = 0; n < 2; ++n) _Pragma("unroll") for (int k = 0; k < 2; ++k) dst[n][k] = *(const PG8_LAS bf16x8*)(lds + PG8_SB(b, h) + boff + n * 2048 + k * 1024); } while (0)
; #define PG8_MMA(ai, bj, At, Bt) do { __builtin_amdgcn_s_setprio(1); _Pragma("unroll") for (int m = 0; m < 4; ++m) _Pragma("unroll") for (int n = 0; n < 2; ++n) _Pragma("unroll") for (int k = 0; k < 2; ++k) \
;         acc[ai][bj][m][n] = __builtin_amdgcn_mfma_f32_16x16x32_bf16(Bt[n][k], At[m][k], acc[ai][bj][m][n], 0, 0, 0); __builtin_amdgcn_s_setprio(0); } while (0)
; #define PG8_WAIT_V(n) asm volatile("s_waitcnt vmcnt(" #n ")" ::: "memory")
; #define PG8_WAIT_L(n) asm volatile("s_waitcnt lgkmcnt(" #n ")" ::: "memory")
; #define PG8_BAR __builtin_amdgcn_s_barrier()
; #define PG8_SCHED __builtin_amdgcn_sched_barrier(0)
; template <class Epi, class Sched, bool ALIGN_EPI = false, bool SP2 = false>
; __device__ __forceinline__ void gemm_phase(PG8_LAS unsigned char* lds, const Gemm g, const Sched& S, const Epi& E) {
;     ...
;             PG8_WAIT_V(8); PG8_WAIT_L(0); PG8_BAR; PG8_MMA(1, 0, At, B0); PG8_MMA(1, 1, At, B1); PG8_BAR; PG8_SCHED;
;             PG8_LDB(B0, 1, 0); PG8_LDB(B1, 1, 1); PG8_SCHED; PG8_LDA(At, 1, 0); PG8_STAGE(PG8_SA(0, 1), a2 + hstep, voffA);
;             PG8_WAIT_V(8); PG8_WAIT_L(0); PG8_BAR; PG8_MMA(0, 0, At, B0); PG8_MMA(0, 1, At, B1); PG8_BAR; PG8_SCHED;
	v_mfma_f32_16x16x32_bf16 v[62:65], v[156:159], v[188:191], 0
	v_mfma_f32_16x16x32_bf16 v[58:61], v[164:167], v[188:191], 0
	v_mfma_f32_16x16x32_bf16 v[46:49], v[156:159], v[196:199], 0
	v_mfma_f32_16x16x32_bf16 v[42:45], v[164:167], v[196:199], 0
	v_mfma_f32_16x16x32_bf16 v[34:37], v[156:159], v[204:207], 0
	v_mfma_f32_16x16x32_bf16 v[26:29], v[164:167], v[204:207], 0
	v_mfma_f32_16x16x32_bf16 v[18:21], v[156:159], v[212:215], 0
	v_mfma_f32_16x16x32_bf16 v[10:13], v[164:167], v[212:215], 0
	v_mfma_f32_16x16x32_bf16 v[62:65], v[160:163], v[192:195], v[62:65]
	v_mfma_f32_16x16x32_bf16 v[58:61], v[168:171], v[192:195], v[58:61]
	v_mfma_f32_16x16x32_bf16 v[46:49], v[160:163], v[200:203], v[46:49]
	v_mfma_f32_16x16x32_bf16 v[42:45], v[168:171], v[200:203], v[42:45]
	v_mfma_f32_16x16x32_bf16 v[34:37], v[160:163], v[208:211], v[34:37]
	v_mfma_f32_16x16x32_bf16 v[26:29], v[168:171], v[208:211], v[26:29]
	v_mfma_f32_16x16x32_bf16 v[18:21], v[160:163], v[220:223], v[18:21]
	v_mfma_f32_16x16x32_bf16 v[10:13], v[168:171], v[220:223], v[10:13]
	s_setprio 0
	s_setprio 1
	v_mfma_f32_16x16x32_bf16 v[54:57], v[172:175], v[188:191], 0
	v_mfma_f32_16x16x32_bf16 v[50:53], v[180:183], v[188:191], 0
	v_mfma_f32_16x16x32_bf16 v[38:41], v[172:175], v[196:199], 0
	v_mfma_f32_16x16x32_bf16 v[30:33], v[180:183], v[196:199], 0
	v_mfma_f32_16x16x32_bf16 v[22:25], v[172:175], v[204:207], 0
	v_mfma_f32_16x16x32_bf16 v[14:17], v[180:183], v[204:207], 0
	v_mfma_f32_16x16x32_bf16 v[6:9], v[172:175], v[212:215], 0
	v_mfma_f32_16x16x32_bf16 v[2:5], v[180:183], v[212:215], 0
	v_mfma_f32_16x16x32_bf16 v[54:57], v[176:179], v[192:195], v[54:57]
	v_mfma_f32_16x16x32_bf16 v[50:53], v[184:187], v[192:195], v[50:53]
	v_mfma_f32_16x16x32_bf16 v[38:41], v[176:179], v[200:203], v[38:41]
	v_mfma_f32_16x16x32_bf16 v[30:33], v[184:187], v[200:203], v[30:33]
	v_mfma_f32_16x16x32_bf16 v[22:25], v[176:179], v[208:211], v[22:25]
	v_mfma_f32_16x16x32_bf16 v[14:17], v[184:187], v[208:211], v[14:17]
	v_mfma_f32_16x16x32_bf16 v[6:9], v[176:179], v[220:223], v[6:9]
	v_mfma_f32_16x16x32_bf16 v[2:5], v[184:187], v[220:223], v[2:5]
	s_barrier
	s_setprio 0
	s_add_i32 s76, 0, 0x18000
	v_add_u32_e32 v148, s76, v149
	s_add_i32 s77, 0, 0x1c000
	ds_read_b128 v[156:159], v148
	ds_read_b128 v[160:163], v148 offset:1024
	ds_read_b128 v[164:167], v148 offset:2048
	ds_read_b128 v[168:171], v148 offset:3072
	v_add_u32_e32 v148, s77, v149
	ds_read_b128 v[172:175], v148
	ds_read_b128 v[176:179], v148 offset:1024
	ds_read_b128 v[180:183], v148 offset:2048
	ds_read_b128 v[184:187], v148 offset:3072
	s_add_u32 s40, s40, 0x4000
	s_addc_u32 s41, s41, 0
	s_mov_b32 m0, s50
	ds_read_b128 v[188:191], v152 offset:32768
	ds_read_b128 v[192:195], v152 offset:33792
	ds_read_b128 v[196:199], v152 offset:34816
	ds_read_b128 v[200:203], v152 offset:35840
	ds_read_b128 v[204:207], v152 offset:36864
	ds_read_b128 v[208:211], v152 offset:37888
	ds_read_b128 v[212:215], v152 offset:38912
	ds_read_b128 v[220:223], v152 offset:39936
	global_load_lds_dwordx4 v136, s[40:41]
	s_mov_b32 m0, s51
	s_nop 0
	global_load_lds_dwordx4 v132, s[40:41]
	s_waitcnt vmcnt(8)
	s_waitcnt lgkmcnt(0)
	s_setprio 1
	s_barrier
	v_mfma_f32_16x16x32_bf16 v[126:129], v[156:159], v[188:191], v[126:129]
	v_mfma_f32_16x16x32_bf16 v[122:125], v[164:167], v[188:191], v[122:125]
	v_mfma_f32_16x16x32_bf16 v[114:117], v[156:159], v[196:199], v[114:117]
	v_mfma_f32_16x16x32_bf16 v[106:109], v[164:167], v[196:199], v[106:109]
	v_mfma_f32_16x16x32_bf16 v[98:101], v[156:159], v[204:207], v[98:101]
	v_mfma_f32_16x16x32_bf16 v[90:93], v[164:167], v[204:207], v[90:93]
	v_mfma_f32_16x16x32_bf16 v[78:81], v[156:159], v[212:215], v[78:81]
	v_mfma_f32_16x16x32_bf16 v[74:77], v[164:167], v[212:215], v[74:77]
	v_mfma_f32_16x16x32_bf16 v[126:129], v[160:163], v[192:195], v[126:129]
	v_mfma_f32_16x16x32_bf16 v[122:125], v[168:171], v[192:195], v[122:125]
	v_mfma_f32_16x16x32_bf16 v[114:117], v[160:163], v[200:203], v[114:117]
	v_mfma_f32_16x16x32_bf16 v[106:109], v[168:171], v[200:203], v[106:109]
	v_mfma_f32_16x16x32_bf16 v[98:101], v[160:163], v[208:211], v[98:101]
	v_mfma_f32_16x16x32_bf16 v[90:93], v[168:171], v[208:211], v[90:93]
	v_mfma_f32_16x16x32_bf16 v[78:81], v[160:163], v[220:223], v[78:81]
	v_mfma_f32_16x16x32_bf16 v[74:77], v[168:171], v[220:223], v[74:77]
	s_setprio 0
	s_setprio 1
	v_mfma_f32_16x16x32_bf16 v[118:121], v[172:175], v[188:191], v[118:121]
	v_mfma_f32_16x16x32_bf16 v[110:113], v[180:183], v[188:191], v[110:113]
	v_mfma_f32_16x16x32_bf16 v[102:105], v[172:175], v[196:199], v[102:105]
	v_mfma_f32_16x16x32_bf16 v[94:97], v[180:183], v[196:199], v[94:97]
	v_mfma_f32_16x16x32_bf16 v[86:89], v[172:175], v[204:207], v[86:89]
	v_mfma_f32_16x16x32_bf16 v[82:85], v[180:183], v[204:207], v[82:85]
	v_mfma_f32_16x16x32_bf16 v[70:73], v[172:175], v[212:215], v[70:73]
	v_mfma_f32_16x16x32_bf16 v[66:69], v[180:183], v[212:215], v[66:69]
	v_mfma_f32_16x16x32_bf16 v[118:121], v[176:179], v[192:195], v[118:121]
	v_mfma_f32_16x16x32_bf16 v[110:113], v[184:187], v[192:195], v[110:113]
	v_mfma_f32_16x16x32_bf16 v[102:105], v[176:179], v[200:203], v[102:105]
	v_mfma_f32_16x16x32_bf16 v[94:97], v[184:187], v[200:203], v[94:97]
	v_mfma_f32_16x16x32_bf16 v[86:89], v[176:179], v[208:211], v[86:89]
	v_mfma_f32_16x16x32_bf16 v[82:85], v[184:187], v[208:211], v[82:85]
	v_mfma_f32_16x16x32_bf16 v[70:73], v[176:179], v[220:223], v[70:73]
	v_mfma_f32_16x16x32_bf16 v[66:69], v[184:187], v[220:223], v[66:69]
	s_barrier
; #define PG8_STAGE(bufoff, gbase, voff) do { _Pragma("unroll") for (int _i = 0; _i < 2; ++_i) \
;         __builtin_amdgcn_global_load_lds((const unsigned*)((const char*)(gbase) + (voff)[_i]), (PG8_LAS unsigned*)(lds + (bufoff) + ldsw + _i * 8192), 16, 0, 0); } while (0)
; #define PG8_LDA(dst, b, h) do { _Pragma("unroll") for (int m = 0; m < 4; ++m) _Pragma("unroll") for (int k = 0; k < 2; ++k) dst[m][k] = *(const PG8_LAS bf16x8*)(lds + PG8_SA(b, h) + aoff + m * 2048 + k * 1024); } while (0)
; #define PG8_MMA(ai, bj, At, Bt) do { __builtin_amdgcn_s_setprio(1); _Pragma("unroll") for (int m = 0; m < 4; ++m) _Pragma("unroll") for (int n = 0; n < 2; ++n) _Pragma("unroll") for (int k = 0; k < 2; ++k) \
;         acc[ai][bj][m][n] = __builtin_amdgcn_mfma_f32_16x16x32_bf16(Bt[n][k], At[m][k], acc[ai][bj][m][n], 0, 0, 0); __builtin_amdgcn_s_setprio(0); } while (0)
; #define PG8_WAIT_V(n) asm volatile("s_waitcnt vmcnt(" #n ")" ::: "memory")
; #define PG8_WAIT_L(n) asm volatile("s_waitcnt lgkmcnt(" #n ")" ::: "memory")
; #define PG8_BAR __builtin_amdgcn_s_barrier()
; #define PG8_SCHED __builtin_amdgcn_sched_barrier(0)
; template <class Epi, class Sched, bool ALIGN_EPI = false, bool SP2 = false>
; __device__ __forceinline__ void gemm_phase(PG8_LAS unsigned char* lds, const Gemm g, const Sched& S, const Epi& E) {
;     ...
;             PG8_LDA(At, 1, 1); PG8_STAGE(PG8_SB(1, 0), b3, voffB); PG8_STAGE(PG8_SB(1, 1), b3 + hstepB, voffB); PG8_STAGE(PG8_SA(1, 0), a3, voffA);
;             PG8_WAIT_V(8); PG8_WAIT_L(0); PG8_BAR; PG8_MMA(1, 0, At, B0); PG8_MMA(1, 1, At, B1); PG8_BAR; PG8_SCHED;
	s_setprio 0
	s_add_u32 s40, s28, 0x8000
	s_addc_u32 s41, s29, 0
	s_add_i32 s76, s76, s0
	s_mov_b32 m0, s76
	ds_read_b128 v[188:191], v152 offset:49152
	ds_read_b128 v[192:195], v152 offset:50176
	ds_read_b128 v[196:199], v152 offset:51200
	ds_read_b128 v[200:203], v152 offset:52224
	ds_read_b128 v[204:207], v152 offset:53248
	ds_read_b128 v[208:211], v152 offset:54272
	ds_read_b128 v[212:215], v152 offset:55296
	ds_read_b128 v[220:223], v152 offset:56320
	global_load_lds_dwordx4 v134, s[40:41]
	s_add_i32 m0, s76, 0x2000
	s_add_u32 s28, s28, 0x9000
	v_lshl_add_u64 v[216:217], s[40:41], 0, v[130:131]
	s_addc_u32 s29, s29, 0
	s_add_i32 s40, s77, s0
	global_load_lds_dwordx4 v[216:217], off
	s_mov_b32 m0, s40
	s_nop 0
	global_load_lds_dwordx4 v134, s[28:29]
	s_add_i32 m0, s40, 0x2000
	s_nop 0
	global_load_lds_dwordx4 v130, s[28:29]
	s_mov_b32 m0, s54
	s_nop 0
	global_load_lds_dwordx4 v136, s[26:27]
	s_mov_b32 m0, s55
	s_nop 0
	global_load_lds_dwordx4 v132, s[26:27]
	s_waitcnt vmcnt(8)
	s_waitcnt lgkmcnt(0)
	s_setprio 1
	s_barrier
	v_mfma_f32_16x16x32_bf16 v[62:65], v[156:159], v[188:191], v[62:65]
	v_mfma_f32_16x16x32_bf16 v[58:61], v[164:167], v[188:191], v[58:61]
	v_mfma_f32_16x16x32_bf16 v[46:49], v[156:159], v[196:199], v[46:49]
	v_mfma_f32_16x16x32_bf16 v[42:45], v[164:167], v[196:199], v[42:45]
	v_mfma_f32_16x16x32_bf16 v[34:37], v[156:159], v[204:207], v[34:37]
	v_mfma_f32_16x16x32_bf16 v[26:29], v[164:167], v[204:207], v[26:29]
	v_mfma_f32_16x16x32_bf16 v[18:21], v[156:159], v[212:215], v[18:21]
	v_mfma_f32_16x16x32_bf16 v[10:13], v[164:167], v[212:215], v[10:13]
	v_mfma_f32_16x16x32_bf16 v[62:65], v[160:163], v[192:195], v[62:65]
	v_mfma_f32_16x16x32_bf16 v[58:61], v[168:171], v[192:195], v[58:61]
	v_mfma_f32_16x16x32_bf16 v[46:49], v[160:163], v[200:203], v[46:49]
	v_mfma_f32_16x16x32_bf16 v[42:45], v[168:171], v[200:203], v[42:45]
	v_mfma_f32_16x16x32_bf16 v[34:37], v[160:163], v[208:211], v[34:37]
	v_mfma_f32_16x16x32_bf16 v[26:29], v[168:171], v[208:211], v[26:29]
	v_mfma_f32_16x16x32_bf16 v[18:21], v[160:163], v[220:223], v[18:21]
	v_mfma_f32_16x16x32_bf16 v[10:13], v[168:171], v[220:223], v[10:13]
	s_setprio 0
	s_setprio 1
	v_mfma_f32_16x16x32_bf16 v[54:57], v[172:175], v[188:191], v[54:57]
	v_mfma_f32_16x16x32_bf16 v[50:53], v[180:183], v[188:191], v[50:53]
	v_mfma_f32_16x16x32_bf16 v[38:41], v[172:175], v[196:199], v[38:41]
	v_mfma_f32_16x16x32_bf16 v[30:33], v[180:183], v[196:199], v[30:33]
	v_mfma_f32_16x16x32_bf16 v[22:25], v[172:175], v[204:207], v[22:25]
	v_mfma_f32_16x16x32_bf16 v[14:17], v[180:183], v[204:207], v[14:17]
	v_mfma_f32_16x16x32_bf16 v[6:9], v[172:175], v[212:215], v[6:9]
	v_mfma_f32_16x16x32_bf16 v[2:5], v[180:183], v[212:215], v[2:5]
	v_mfma_f32_16x16x32_bf16 v[54:57], v[176:179], v[192:195], v[54:57]
	v_mfma_f32_16x16x32_bf16 v[50:53], v[184:187], v[192:195], v[50:53]
	v_mfma_f32_16x16x32_bf16 v[38:41], v[176:179], v[200:203], v[38:41]
	v_mfma_f32_16x16x32_bf16 v[30:33], v[184:187], v[200:203], v[30:33]
	v_mfma_f32_16x16x32_bf16 v[22:25], v[176:179], v[208:211], v[22:25]
	v_mfma_f32_16x16x32_bf16 v[14:17], v[184:187], v[208:211], v[14:17]
	v_mfma_f32_16x16x32_bf16 v[6:9], v[176:179], v[220:223], v[6:9]
	v_mfma_f32_16x16x32_bf16 v[2:5], v[184:187], v[220:223], v[2:5]
	s_barrier
	s_setprio 0
	s_add_i32 s75, s75, 2
	s_add_u32 s24, s24, 0x10000
	s_addc_u32 s25, s25, 0
	s_add_u32 s73, s73, 0x10000
	s_addc_u32 s74, s74, 0

; #define PG8_STAGE(bufoff, gbase, voff) do { _Pragma("unroll") for (int _i = 0; _i < 2; ++_i) \
;         __builtin_amdgcn_global_load_lds((const unsigned*)((const char*)(gbase) + (voff)[_i]), (PG8_LAS unsigned*)(lds + (bufoff) + ldsw + _i * 8192), 16, 0, 0); } while (0)
; #define PG8_LDA(dst, b, h) do { _Pragma("unroll") for (int m = 0; m < 4; ++m) _Pragma("unroll") for (int k = 0; k < 2; ++k) dst[m][k] = *(const PG8_LAS bf16x8*)(lds + PG8_SA(b, h) + aoff + m * 2048 + k * 1024); } while (0)
; #define PG8_LDB(dst, b, h) do { _Pragma("unroll") for (int n = 0; n < 2; ++n) _Pragma("unroll") for (int k = 0; k < 2; ++k) dst[n][k] = *(const PG8_LAS bf16x8*)(lds + PG8_SB(b, h) + boff + n * 2048 + k * 1024); } while (0)
; #define PG8_MMA(ai, bj, At, Bt) do { __builtin_amdgcn_s_setprio(1); _Pragma("unroll") for (int m = 0; m < 4; ++m) _Pragma("unroll") for (int n = 0; n < 2; ++n) _Pragma("unroll") for (int k = 0; k < 2; ++k) \
;         acc[ai][bj][m][n] = __builtin_amdgcn_mfma_f32_16x16x32_bf16(Bt[n][k], At[m][k], acc[ai][bj][m][n], 0, 0, 0); __builtin_amdgcn_s_setprio(0); } while (0)
; template <class Epi, class Sched, bool ALIGN_EPI = false, bool SP2 = false>
; __device__ __forceinline__ void gemm_phase(PG8_LAS unsigned char* lds, const Gemm g, const Sched& S, const Epi& E) {
;     ...
;         const char* nA = has_next ? (const char*)g.A + (size_t)nxt.pm * tstep : cA; const char* nB = has_next ? (const char*)g.Bt + (size_t)nxt.pn * tstep : cB;
;         for (int t = 0; t < nt; t += 2) {
;             if constexpr (Epi::HAS_MID) { if (t == (nt >> 1)) E.mid(acc, cur, wr, wc, fr, fq); }
;             const bool last = (t == nt - 2);
;             const char* a1 = cA + (size_t)(t + 1) * kstep;
;             const char* a2 = last ? nA : cA + (size_t)(t + 2) * kstep; const char* b2 = last ? nB : cB + (size_t)(t + 2) * kstep;
;             const char* a3 = a2 + kstep; const char* b3 = b2 + kstep;
;             if (last && has_next) S.a_ready(nxt);
;             if constexpr (SP2) {
;             PG8_LDB(B0, 0, 0); PG8_LDB(B1, 0, 1); PG8_SCHED; PG8_LDA(At, 0, 0); PG8_STAGE(PG8_SA(1, 1), a1 + hstep, voffA);
;             PG8_WAIT_V(8); PG8_WAIT_L(0); PG8_BAR; PG8_MMA(0, 0, At, B0); PG8_MMA(0, 1, At, B1); PG8_BAR; PG8_SCHED;
;             PG8_LDA(At, 0, 1); PG8_STAGE(PG8_SB(0, 0), b2, voffB); PG8_STAGE(PG8_SB(0, 1), b2 + hstepB, voffB); PG8_STAGE(PG8_SA(0, 0), a2, voffA);
.LBB0_476:
	s_ashr_i32 s29, s28, 31
	s_lshl_b64 s[42:43], s[28:29], 19
	s_add_u32 s42, s3, s42
	s_addc_u32 s43, s76, s43
	s_and_b64 s[44:45], s[4:5], exec
	s_cselect_b32 s29, s43, s51
	s_cselect_b32 s47, s42, s50
	s_ashr_i32 s27, s26, 31
	s_lshl_b64 s[44:45], s[26:27], 19
	s_add_u32 s44, s66, s44
	s_addc_u32 s45, s67, s45
	s_and_b64 s[52:53], s[4:5], exec
	s_cselect_b32 s27, s45, s69
	s_cselect_b32 s52, s44, s68
	s_add_u32 s50, s50, 0xc000
	s_addc_u32 s51, s51, 0
	s_add_u32 s53, s68, 0x10000
	s_addc_u32 s54, s69, 0
	s_mov_b32 s55, -2
	s_waitcnt lgkmcnt(0)
	ds_read_b128 v[130:133], v201
	ds_read_b128 v[134:137], v201 offset:1024
	ds_read_b128 v[138:141], v201 offset:2048
	ds_read_b128 v[142:145], v201 offset:3072
	ds_read_b128 v[146:149], v202
	ds_read_b128 v[150:153], v202 offset:1024
	ds_read_b128 v[154:157], v202 offset:2048
	ds_read_b128 v[158:161], v202 offset:3072
	s_add_u32 s68, s50, 0x4000
	s_addc_u32 s69, s51, 0
	s_cmp_eq_u32 s55, 12
	s_cselect_b32 s72, s47, s68
	s_cselect_b32 s73, s29, s69
	s_cselect_b32 s70, s52, s53
	s_cselect_b32 s71, s27, s54
	s_add_u32 s68, s72, 0x8000
	s_addc_u32 s69, s73, 0
	s_add_i32 m0, s1, 0xc000
	ds_read_b128 v[162:165], v203
	ds_read_b128 v[166:169], v203 offset:1024
	ds_read_b128 v[170:173], v203 offset:2048
	ds_read_b128 v[174:177], v203 offset:3072
	ds_read_b128 v[208:211], v203 offset:4096
	ds_read_b128 v[212:215], v203 offset:5120
	ds_read_b128 v[220:223], v203 offset:6144
	ds_read_b128 v[224:227], v203 offset:7168
	global_load_lds_dwordx4 v188, s[50:51]
	s_add_i32 m0, s1, 0xe000
	s_nop 0
	global_load_lds_dwordx4 v190, s[50:51]
	s_waitcnt vmcnt(8)
	s_waitcnt lgkmcnt(0)
	s_setprio 1
	s_barrier
	v_mfma_f32_16x16x32_bf16 v[126:129], v[130:133], v[162:165], 0
	v_mfma_f32_16x16x32_bf16 v[122:125], v[138:141], v[162:165], 0
	v_mfma_f32_16x16x32_bf16 v[110:113], v[130:133], v[170:173], 0
	v_mfma_f32_16x16x32_bf16 v[106:109], v[138:141], v[170:173], 0
	v_mfma_f32_16x16x32_bf16 v[94:97], v[130:133], v[208:211], 0
	v_mfma_f32_16x16x32_bf16 v[90:93], v[138:141], v[208:211], 0
	v_mfma_f32_16x16x32_bf16 v[78:81], v[130:133], v[220:223], 0
	v_mfma_f32_16x16x32_bf16 v[74:77], v[138:141], v[220:223], 0
	v_mfma_f32_16x16x32_bf16 v[126:129], v[134:137], v[166:169], v[126:129]
	v_mfma_f32_16x16x32_bf16 v[122:125], v[142:145], v[166:169], v[122:125]
	v_mfma_f32_16x16x32_bf16 v[110:113], v[134:137], v[174:177], v[110:113]
	v_mfma_f32_16x16x32_bf16 v[106:109], v[142:145], v[174:177], v[106:109]
	v_mfma_f32_16x16x32_bf16 v[94:97], v[134:137], v[212:215], v[94:97]
	v_mfma_f32_16x16x32_bf16 v[90:93], v[142:145], v[212:215], v[90:93]
	v_mfma_f32_16x16x32_bf16 v[78:81], v[134:137], v[224:227], v[78:81]
	v_mfma_f32_16x16x32_bf16 v[74:77], v[142:145], v[224:227], v[74:77]
	s_setprio 0
	s_setprio 1
	v_mfma_f32_16x16x32_bf16 v[118:121], v[146:149], v[162:165], 0
	v_mfma_f32_16x16x32_bf16 v[114:117], v[154:157], v[162:165], 0
	v_mfma_f32_16x16x32_bf16 v[102:105], v[146:149], v[170:173], 0
	v_mfma_f32_16x16x32_bf16 v[98:101], v[154:157], v[170:173], 0
	v_mfma_f32_16x16x32_bf16 v[86:89], v[146:149], v[208:211], 0
	v_mfma_f32_16x16x32_bf16 v[82:85], v[154:157], v[208:211], 0
	v_mfma_f32_16x16x32_bf16 v[70:73], v[146:149], v[220:223], 0
	v_mfma_f32_16x16x32_bf16 v[66:69], v[154:157], v[220:223], 0
	v_mfma_f32_16x16x32_bf16 v[118:121], v[150:153], v[166:169], v[118:121]
	v_mfma_f32_16x16x32_bf16 v[114:117], v[158:161], v[166:169], v[114:117]
	v_mfma_f32_16x16x32_bf16 v[102:105], v[150:153], v[174:177], v[102:105]
	v_mfma_f32_16x16x32_bf16 v[98:101], v[158:161], v[174:177], v[98:101]
	v_mfma_f32_16x16x32_bf16 v[86:89], v[150:153], v[212:215], v[86:89]
	v_mfma_f32_16x16x32_bf16 v[82:85], v[158:161], v[212:215], v[82:85]
	v_mfma_f32_16x16x32_bf16 v[70:73], v[150:153], v[224:227], v[70:73]
	v_mfma_f32_16x16x32_bf16 v[66:69], v[158:161], v[224:227], v[66:69]
	s_barrier
	s_setprio 0
	s_add_i32 s79, s77, s0
	s_mov_b32 m0, s79
	ds_read_b128 v[162:165], v203 offset:16384
	ds_read_b128 v[166:169], v203 offset:17408
	ds_read_b128 v[170:173], v203 offset:18432
	ds_read_b128 v[174:177], v203 offset:19456
	ds_read_b128 v[208:211], v203 offset:20480
	ds_read_b128 v[212:215], v203 offset:21504
	ds_read_b128 v[220:223], v203 offset:22528
	ds_read_b128 v[224:227], v203 offset:23552
	global_load_lds_dwordx4 v180, s[70:71]
	s_add_i32 m0, s79, 0x2000
	s_add_u32 s80, s70, 0x1000
	s_addc_u32 s81, s71, 0
	s_add_i32 s79, s78, s0
	global_load_lds_dwordx4 v184, s[70:71]
	s_mov_b32 m0, s79
	s_nop 0
	global_load_lds_dwordx4 v180, s[80:81]
	s_add_i32 m0, s79, 0x2000
	s_nop 0
	global_load_lds_dwordx4 v184, s[80:81]
	s_mov_b32 m0, s1
	s_nop 0
	global_load_lds_dwordx4 v178, s[72:73]
	s_mov_b32 m0, s49
	s_nop 0
	global_load_lds_dwordx4 v182, s[72:73]
	s_waitcnt vmcnt(8)
	s_waitcnt lgkmcnt(0)
	s_setprio 1
	s_barrier
; #define PG8_STAGE(bufoff, gbase, voff) do { _Pragma("unroll") for (int _i = 0; _i < 2; ++_i) \
;         __builtin_amdgcn_global_load_lds((const unsigned*)((const char*)(gbase) + (voff)[_i]), (PG8_LAS unsigned*)(lds + (bufoff) + ldsw + _i * 8192), 16, 0, 0); } while (0)
; #define PG8_LDA(dst, b, h) do { _Pragma("unroll") for (int m = 0; m < 4; ++m) _Pragma("unroll") for (int k = 0; k < 2; ++k) dst[m][k] = *(const PG8_LAS bf16x8*)(lds + PG8_SA(b, h) + aoff + m * 2048 + k * 1024); } while (0)
; #define PG8_LDB(dst, b, h) do { _Pragma("unroll") for (int n = 0; n < 2; ++n) _Pragma("unroll") for (int k = 0; k < 2; ++k) dst[n][k] = *(const PG8_LAS bf16x8*)(lds + PG8_SB(b, h) + boff + n * 2048 + k * 1024); } while (0)
; #define PG8_MMA(ai, bj, At, Bt) do { __builtin_amdgcn_s_setprio(1); _Pragma("unroll") for (int m = 0; m < 4; ++m) _Pragma("unroll") for (int n = 0; n < 2; ++n) _Pragma("unroll") for (int k = 0; k < 2; ++k) \
;         acc[ai][bj][m][n] = __builtin_amdgcn_mfma_f32_16x16x32_bf16(Bt[n][k], At[m][k], acc[ai][bj][m][n], 0, 0, 0); __builtin_amdgcn_s_setprio(0); } while (0)
; #define PG8_WAIT_V(n) asm volatile("s_waitcnt vmcnt(" #n ")" ::: "memory")
; #define PG8_WAIT_L(n) asm volatile("s_waitcnt lgkmcnt(" #n ")" ::: "memory")
; #define PG8_BAR __builtin_amdgcn_s_barrier()
; #define PG8_SCHED __builtin_amdgcn_sched_barrier(0)
; template <class Epi, class Sched, bool ALIGN_EPI = false, bool SP2 = false>
; __device__ __forceinline__ void gemm_phase(PG8_LAS unsigned char* lds, const Gemm g, const Sched& S, const Epi& E) {
;     ...
;             PG8_WAIT_V(8); PG8_WAIT_L(0); PG8_BAR; PG8_MMA(1, 0, At, B0); PG8_MMA(1, 1, At, B1); PG8_BAR; PG8_SCHED;
;             PG8_LDB(B0, 1, 0); PG8_LDB(B1, 1, 1); PG8_SCHED; PG8_LDA(At, 1, 0); PG8_STAGE(PG8_SA(0, 1), a2 + hstep, voffA);
;             PG8_WAIT_V(8); PG8_WAIT_L(0); PG8_BAR; PG8_MMA(0, 0, At, B0); PG8_MMA(0, 1, At, B1); PG8_BAR; PG8_SCHED;
	v_mfma_f32_16x16x32_bf16 v[62:65], v[130:133], v[162:165], 0
	v_mfma_f32_16x16x32_bf16 v[58:61], v[138:141], v[162:165], 0
	v_mfma_f32_16x16x32_bf16 v[46:49], v[130:133], v[170:173], 0
	v_mfma_f32_16x16x32_bf16 v[42:45], v[138:141], v[170:173], 0
	v_mfma_f32_16x16x32_bf16 v[30:33], v[130:133], v[208:211], 0
	v_mfma_f32_16x16x32_bf16 v[26:29], v[138:141], v[208:211], 0
	v_mfma_f32_16x16x32_bf16 v[14:17], v[130:133], v[220:223], 0
	v_mfma_f32_16x16x32_bf16 v[10:13], v[138:141], v[220:223], 0
	v_mfma_f32_16x16x32_bf16 v[62:65], v[134:137], v[166:169], v[62:65]
	v_mfma_f32_16x16x32_bf16 v[58:61], v[142:145], v[166:169], v[58:61]
	v_mfma_f32_16x16x32_bf16 v[46:49], v[134:137], v[174:177], v[46:49]
	v_mfma_f32_16x16x32_bf16 v[42:45], v[142:145], v[174:177], v[42:45]
	v_mfma_f32_16x16x32_bf16 v[30:33], v[134:137], v[212:215], v[30:33]
	v_mfma_f32_16x16x32_bf16 v[26:29], v[142:145], v[212:215], v[26:29]
	v_mfma_f32_16x16x32_bf16 v[14:17], v[134:137], v[224:227], v[14:17]
	v_mfma_f32_16x16x32_bf16 v[10:13], v[142:145], v[224:227], v[10:13]
	s_setprio 0
	s_setprio 1
	v_mfma_f32_16x16x32_bf16 v[54:57], v[146:149], v[162:165], 0
	v_mfma_f32_16x16x32_bf16 v[50:53], v[154:157], v[162:165], 0
	v_mfma_f32_16x16x32_bf16 v[38:41], v[146:149], v[170:173], 0
	v_mfma_f32_16x16x32_bf16 v[34:37], v[154:157], v[170:173], 0
	v_mfma_f32_16x16x32_bf16 v[22:25], v[146:149], v[208:211], 0
	v_mfma_f32_16x16x32_bf16 v[18:21], v[154:157], v[208:211], 0
	v_mfma_f32_16x16x32_bf16 v[6:9], v[146:149], v[220:223], 0
	v_mfma_f32_16x16x32_bf16 v[2:5], v[154:157], v[220:223], 0
	v_mfma_f32_16x16x32_bf16 v[54:57], v[150:153], v[166:169], v[54:57]
	v_mfma_f32_16x16x32_bf16 v[50:53], v[158:161], v[166:169], v[50:53]
	v_mfma_f32_16x16x32_bf16 v[38:41], v[150:153], v[174:177], v[38:41]
	v_mfma_f32_16x16x32_bf16 v[34:37], v[158:161], v[174:177], v[34:37]
	v_mfma_f32_16x16x32_bf16 v[22:25], v[150:153], v[212:215], v[22:25]
	v_mfma_f32_16x16x32_bf16 v[18:21], v[158:161], v[212:215], v[18:21]
	v_mfma_f32_16x16x32_bf16 v[6:9], v[150:153], v[224:227], v[6:9]
	v_mfma_f32_16x16x32_bf16 v[2:5], v[158:161], v[224:227], v[2:5]
	s_barrier
	s_setprio 0
	s_add_i32 s79, 0, 0x18000
	s_add_i32 s80, 0, 0x1c000
	v_add_u32_e32 v142, s79, v199
	v_add_u32_e32 v158, s80, v199
	ds_read_b128 v[130:133], v142
	ds_read_b128 v[134:137], v142 offset:1024
	ds_read_b128 v[138:141], v142 offset:2048
	ds_read_b128 v[142:145], v142 offset:3072
	ds_read_b128 v[146:149], v158
	ds_read_b128 v[150:153], v158 offset:1024
	ds_read_b128 v[154:157], v158 offset:2048
	ds_read_b128 v[158:161], v158 offset:3072
	s_add_u32 s72, s72, 0x4000
	s_addc_u32 s73, s73, 0
	s_mov_b32 m0, s56
	ds_read_b128 v[162:165], v203 offset:32768
	ds_read_b128 v[166:169], v203 offset:33792
	ds_read_b128 v[170:173], v203 offset:34816
	ds_read_b128 v[174:177], v203 offset:35840
	ds_read_b128 v[208:211], v203 offset:36864
	ds_read_b128 v[212:215], v203 offset:37888
	ds_read_b128 v[220:223], v203 offset:38912
	ds_read_b128 v[224:227], v203 offset:39936
	global_load_lds_dwordx4 v178, s[72:73]
	s_mov_b32 m0, s57
	s_nop 0
	global_load_lds_dwordx4 v182, s[72:73]
	s_waitcnt vmcnt(8)
	s_waitcnt lgkmcnt(0)
	s_setprio 1
	s_barrier
	v_mfma_f32_16x16x32_bf16 v[126:129], v[130:133], v[162:165], v[126:129]
	v_mfma_f32_16x16x32_bf16 v[122:125], v[138:141], v[162:165], v[122:125]
	v_mfma_f32_16x16x32_bf16 v[110:113], v[130:133], v[170:173], v[110:113]
	v_mfma_f32_16x16x32_bf16 v[106:109], v[138:141], v[170:173], v[106:109]
	v_mfma_f32_16x16x32_bf16 v[94:97], v[130:133], v[208:211], v[94:97]
	v_mfma_f32_16x16x32_bf16 v[90:93], v[138:141], v[208:211], v[90:93]
	v_mfma_f32_16x16x32_bf16 v[78:81], v[130:133], v[220:223], v[78:81]
	v_mfma_f32_16x16x32_bf16 v[74:77], v[138:141], v[220:223], v[74:77]
	v_mfma_f32_16x16x32_bf16 v[126:129], v[134:137], v[166:169], v[126:129]
	v_mfma_f32_16x16x32_bf16 v[122:125], v[142:145], v[166:169], v[122:125]
	v_mfma_f32_16x16x32_bf16 v[110:113], v[134:137], v[174:177], v[110:113]
	v_mfma_f32_16x16x32_bf16 v[106:109], v[142:145], v[174:177], v[106:109]
	v_mfma_f32_16x16x32_bf16 v[94:97], v[134:137], v[212:215], v[94:97]
	v_mfma_f32_16x16x32_bf16 v[90:93], v[142:145], v[212:215], v[90:93]
	v_mfma_f32_16x16x32_bf16 v[78:81], v[134:137], v[224:227], v[78:81]
	v_mfma_f32_16x16x32_bf16 v[74:77], v[142:145], v[224:227], v[74:77]
	s_setprio 0
	s_setprio 1
	v_mfma_f32_16x16x32_bf16 v[118:121], v[146:149], v[162:165], v[118:121]
	v_mfma_f32_16x16x32_bf16 v[114:117], v[154:157], v[162:165], v[114:117]
	v_mfma_f32_16x16x32_bf16 v[102:105], v[146:149], v[170:173], v[102:105]
	v_mfma_f32_16x16x32_bf16 v[98:101], v[154:157], v[170:173], v[98:101]
	v_mfma_f32_16x16x32_bf16 v[86:89], v[146:149], v[208:211], v[86:89]
	v_mfma_f32_16x16x32_bf16 v[82:85], v[154:157], v[208:211], v[82:85]
	v_mfma_f32_16x16x32_bf16 v[70:73], v[146:149], v[220:223], v[70:73]
	v_mfma_f32_16x16x32_bf16 v[66:69], v[154:157], v[220:223], v[66:69]
	v_mfma_f32_16x16x32_bf16 v[118:121], v[150:153], v[166:169], v[118:121]
	v_mfma_f32_16x16x32_bf16 v[114:117], v[158:161], v[166:169], v[114:117]
	v_mfma_f32_16x16x32_bf16 v[102:105], v[150:153], v[174:177], v[102:105]
	v_mfma_f32_16x16x32_bf16 v[98:101], v[158:161], v[174:177], v[98:101]
	v_mfma_f32_16x16x32_bf16 v[86:89], v[150:153], v[212:215], v[86:89]
	v_mfma_f32_16x16x32_bf16 v[82:85], v[158:161], v[212:215], v[82:85]
	v_mfma_f32_16x16x32_bf16 v[70:73], v[150:153], v[224:227], v[70:73]
	v_mfma_f32_16x16x32_bf16 v[66:69], v[158:161], v[224:227], v[66:69]
	s_barrier
; #define PG8_STAGE(bufoff, gbase, voff) do { _Pragma("unroll") for (int _i = 0; _i < 2; ++_i) \
;         __builtin_amdgcn_global_load_lds((const unsigned*)((const char*)(gbase) + (voff)[_i]), (PG8_LAS unsigned*)(lds + (bufoff) + ldsw + _i * 8192), 16, 0, 0); } while (0)
; #define PG8_LDA(dst, b, h) do { _Pragma("unroll") for (int m = 0; m < 4; ++m) _Pragma("unroll") for (int k = 0; k < 2; ++k) dst[m][k] = *(const PG8_LAS bf16x8*)(lds + PG8_SA(b, h) + aoff + m * 2048 + k * 1024); } while (0)
; #define PG8_MMA(ai, bj, At, Bt) do { __builtin_amdgcn_s_setprio(1); _Pragma("unroll") for (int m = 0; m < 4; ++m) _Pragma("unroll") for (int n = 0; n < 2; ++n) _Pragma("unroll") for (int k = 0; k < 2; ++k) \
;         acc[ai][bj][m][n] = __builtin_amdgcn_mfma_f32_16x16x32_bf16(Bt[n][k], At[m][k], acc[ai][bj][m][n], 0, 0, 0); __builtin_amdgcn_s_setprio(0); } while (0)
; #define PG8_WAIT_V(n) asm volatile("s_waitcnt vmcnt(" #n ")" ::: "memory")
; #define PG8_WAIT_L(n) asm volatile("s_waitcnt lgkmcnt(" #n ")" ::: "memory")
; #define PG8_BAR __builtin_amdgcn_s_barrier()
; #define PG8_SCHED __builtin_amdgcn_sched_barrier(0)
; template <class Epi, class Sched, bool ALIGN_EPI = false, bool SP2 = false>
; __device__ __forceinline__ void gemm_phase(PG8_LAS unsigned char* lds, const Gemm g, const Sched& S, const Epi& E) {
;     ...
;             PG8_LDA(At, 1, 1); PG8_STAGE(PG8_SB(1, 0), b3, voffB); PG8_STAGE(PG8_SB(1, 1), b3 + hstepB, voffB); PG8_STAGE(PG8_SA(1, 0), a3, voffA);
;             PG8_WAIT_V(8); PG8_WAIT_L(0); PG8_BAR; PG8_MMA(1, 0, At, B0); PG8_MMA(1, 1, At, B1); PG8_BAR; PG8_SCHED;
	s_setprio 0
	s_add_u32 s72, s70, 0x8000
	s_addc_u32 s73, s71, 0
	s_add_i32 s79, s79, s0
	s_mov_b32 m0, s79
	ds_read_b128 v[162:165], v203 offset:49152
	ds_read_b128 v[166:169], v203 offset:50176
	ds_read_b128 v[170:173], v203 offset:51200
	ds_read_b128 v[174:177], v203 offset:52224
	ds_read_b128 v[208:211], v203 offset:53248
	ds_read_b128 v[212:215], v203 offset:54272
	ds_read_b128 v[220:223], v203 offset:55296
	ds_read_b128 v[224:227], v203 offset:56320
	global_load_lds_dwordx4 v180, s[72:73]
	s_add_i32 m0, s79, 0x2000
	s_add_u32 s70, s70, 0x9000
	v_lshl_add_u64 v[196:197], s[72:73], 0, v[184:185]
	s_addc_u32 s71, s71, 0
	s_add_i32 s72, s80, s0
	global_load_lds_dwordx4 v[196:197], off
	s_mov_b32 m0, s72
	s_nop 0
	global_load_lds_dwordx4 v180, s[70:71]
	s_add_i32 m0, s72, 0x2000
	s_nop 0
	global_load_lds_dwordx4 v184, s[70:71]
	s_mov_b32 m0, s59
	s_nop 0
	global_load_lds_dwordx4 v178, s[68:69]
	s_mov_b32 m0, s74
	s_nop 0
	global_load_lds_dwordx4 v182, s[68:69]
	s_waitcnt vmcnt(8)
	s_waitcnt lgkmcnt(0)
	s_setprio 1
	s_barrier
	v_mfma_f32_16x16x32_bf16 v[62:65], v[130:133], v[162:165], v[62:65]
	v_mfma_f32_16x16x32_bf16 v[58:61], v[138:141], v[162:165], v[58:61]
	v_mfma_f32_16x16x32_bf16 v[46:49], v[130:133], v[170:173], v[46:49]
	v_mfma_f32_16x16x32_bf16 v[42:45], v[138:141], v[170:173], v[42:45]
	v_mfma_f32_16x16x32_bf16 v[30:33], v[130:133], v[208:211], v[30:33]
	v_mfma_f32_16x16x32_bf16 v[26:29], v[138:141], v[208:211], v[26:29]
	v_mfma_f32_16x16x32_bf16 v[14:17], v[130:133], v[220:223], v[14:17]
	v_mfma_f32_16x16x32_bf16 v[10:13], v[138:141], v[220:223], v[10:13]
	v_mfma_f32_16x16x32_bf16 v[62:65], v[134:137], v[166:169], v[62:65]
	v_mfma_f32_16x16x32_bf16 v[58:61], v[142:145], v[166:169], v[58:61]
	v_mfma_f32_16x16x32_bf16 v[46:49], v[134:137], v[174:177], v[46:49]
	v_mfma_f32_16x16x32_bf16 v[42:45], v[142:145], v[174:177], v[42:45]
	v_mfma_f32_16x16x32_bf16 v[30:33], v[134:137], v[212:215], v[30:33]
	v_mfma_f32_16x16x32_bf16 v[26:29], v[142:145], v[212:215], v[26:29]
	v_mfma_f32_16x16x32_bf16 v[14:17], v[134:137], v[224:227], v[14:17]
	v_mfma_f32_16x16x32_bf16 v[10:13], v[142:145], v[224:227], v[10:13]
	s_setprio 0
	s_setprio 1
	v_mfma_f32_16x16x32_bf16 v[54:57], v[146:149], v[162:165], v[54:57]
	v_mfma_f32_16x16x32_bf16 v[50:53], v[154:157], v[162:165], v[50:53]
	v_mfma_f32_16x16x32_bf16 v[38:41], v[146:149], v[170:173], v[38:41]
	v_mfma_f32_16x16x32_bf16 v[34:37], v[154:157], v[170:173], v[34:37]
	v_mfma_f32_16x16x32_bf16 v[22:25], v[146:149], v[208:211], v[22:25]
	v_mfma_f32_16x16x32_bf16 v[18:21], v[154:157], v[208:211], v[18:21]
	v_mfma_f32_16x16x32_bf16 v[6:9], v[146:149], v[220:223], v[6:9]
	v_mfma_f32_16x16x32_bf16 v[2:5], v[154:157], v[220:223], v[2:5]
	v_mfma_f32_16x16x32_bf16 v[54:57], v[150:153], v[166:169], v[54:57]
	v_mfma_f32_16x16x32_bf16 v[50:53], v[158:161], v[166:169], v[50:53]
	v_mfma_f32_16x16x32_bf16 v[38:41], v[150:153], v[174:177], v[38:41]
	v_mfma_f32_16x16x32_bf16 v[34:37], v[158:161], v[174:177], v[34:37]
	v_mfma_f32_16x16x32_bf16 v[22:25], v[150:153], v[212:215], v[22:25]
	v_mfma_f32_16x16x32_bf16 v[18:21], v[158:161], v[212:215], v[18:21]
	v_mfma_f32_16x16x32_bf16 v[6:9], v[150:153], v[224:227], v[6:9]
	v_mfma_f32_16x16x32_bf16 v[2:5], v[158:161], v[224:227], v[2:5]
	s_barrier
	s_setprio 0
	s_add_i32 s55, s55, 2
	s_add_u32 s50, s50, 0x10000
	s_addc_u32 s51, s51, 0
	s_add_u32 s53, s53, 0x10000
	s_addc_u32 s54, s54, 0

; #define PG8_STAGE(bufoff, gbase, voff) do { _Pragma("unroll") for (int _i = 0; _i < 2; ++_i) \
;         __builtin_amdgcn_global_load_lds((const unsigned*)((const char*)(gbase) + (voff)[_i]), (PG8_LAS unsigned*)(lds + (bufoff) + ldsw + _i * 8192), 16, 0, 0); } while (0)
; #define PG8_LDA(dst, b, h) do { _Pragma("unroll") for (int m = 0; m < 4; ++m) _Pragma("unroll") for (int k = 0; k < 2; ++k) dst[m][k] = *(const PG8_LAS bf16x8*)(lds + PG8_SA(b, h) + aoff + m * 2048 + k * 1024); } while (0)
; #define PG8_LDB(dst, b, h) do { _Pragma("unroll") for (int n = 0; n < 2; ++n) _Pragma("unroll") for (int k = 0; k < 2; ++k) dst[n][k] = *(const PG8_LAS bf16x8*)(lds + PG8_SB(b, h) + boff + n * 2048 + k * 1024); } while (0)
; #define PG8_MMA(ai, bj, At, Bt) do { __builtin_amdgcn_s_setprio(1); _Pragma("unroll") for (int m = 0; m < 4; ++m) _Pragma("unroll") for (int n = 0; n < 2; ++n) _Pragma("unroll") for (int k = 0; k < 2; ++k) \
;         acc[ai][bj][m][n] = __builtin_amdgcn_mfma_f32_16x16x32_bf16(Bt[n][k], At[m][k], acc[ai][bj][m][n], 0, 0, 0); __builtin_amdgcn_s_setprio(0); } while (0)
; template <class Epi, class Sched, bool ALIGN_EPI = false, bool SP2 = false>
; __device__ __forceinline__ void gemm_phase(PG8_LAS unsigned char* lds, const Gemm g, const Sched& S, const Epi& E) {
;     ...
;         const char* nA = has_next ? (const char*)g.A + (size_t)nxt.pm * tstep : cA; const char* nB = has_next ? (const char*)g.Bt + (size_t)nxt.pn * tstep : cB;
;         for (int t = 0; t < nt; t += 2) {
;             if constexpr (Epi::HAS_MID) { if (t == (nt >> 1)) E.mid(acc, cur, wr, wc, fr, fq); }
;             const bool last = (t == nt - 2);
;             const char* a1 = cA + (size_t)(t + 1) * kstep;
;             const char* a2 = last ? nA : cA + (size_t)(t + 2) * kstep; const char* b2 = last ? nB : cB + (size_t)(t + 2) * kstep;
;             const char* a3 = a2 + kstep; const char* b3 = b2 + kstep;
;             if (last && has_next) S.a_ready(nxt);
;             if constexpr (SP2) {
;             PG8_LDB(B0, 0, 0); PG8_LDB(B1, 0, 1); PG8_SCHED; PG8_LDA(At, 0, 0); PG8_STAGE(PG8_SA(1, 1), a1 + hstep, voffA);
;             PG8_WAIT_V(8); PG8_WAIT_L(0); PG8_BAR; PG8_MMA(0, 0, At, B0); PG8_MMA(0, 1, At, B1); PG8_BAR; PG8_SCHED;
;             PG8_LDA(At, 0, 1); PG8_STAGE(PG8_SB(0, 0), b2, voffB); PG8_STAGE(PG8_SB(0, 1), b2 + hstepB, voffB); PG8_STAGE(PG8_SA(0, 0), a2, voffA);
.LBB0_585:
	s_ashr_i32 s19, s18, 31
	s_lshl_b64 s[20:21], s[18:19], 19
	s_add_u32 s20, s62, s20
	s_addc_u32 s21, s63, s21
	s_and_b64 s[22:23], s[4:5], exec
	s_cselect_b32 s19, s21, s27
	s_cselect_b32 s55, s20, s26
	s_ashr_i32 s17, s16, 31
	s_lshl_b64 s[22:23], s[16:17], 19
	s_add_u32 s22, s64, s22
	s_addc_u32 s23, s65, s23
	s_and_b64 s[36:37], s[4:5], exec
	s_cselect_b32 s17, s23, s29
	s_cselect_b32 s56, s22, s28
	s_add_u32 s26, s26, 0xc000
	s_addc_u32 s27, s27, 0
	s_add_u32 s57, s28, 0x10000
	s_addc_u32 s58, s29, 0
	s_mov_b32 s59, -2
	ds_read_b128 v[166:169], v153
	ds_read_b128 v[170:173], v153 offset:1024
	ds_read_b128 v[174:177], v153 offset:2048
	ds_read_b128 v[178:181], v153 offset:3072
	ds_read_b128 v[182:185], v154
	ds_read_b128 v[186:189], v154 offset:1024
	ds_read_b128 v[190:193], v154 offset:2048
	ds_read_b128 v[194:197], v154 offset:3072
	s_add_u32 s28, s26, 0x4000
	s_addc_u32 s29, s27, 0
	s_cmp_eq_u32 s59, 12
	s_cselect_b32 s42, s55, s28
	s_cselect_b32 s43, s19, s29
	s_cselect_b32 s36, s56, s57
	s_cselect_b32 s37, s17, s58
	s_add_u32 s28, s42, 0x8000
	s_addc_u32 s29, s43, 0
	s_add_i32 m0, s3, 0xc000
	ds_read_b128 v[198:201], v155
	ds_read_b128 v[202:205], v155 offset:1024
	ds_read_b128 v[206:209], v155 offset:2048
	ds_read_b128 v[210:213], v155 offset:3072
	ds_read_b128 v[214:217], v155 offset:4096
	ds_read_b128 v[220:223], v155 offset:5120
	ds_read_b128 v[224:227], v155 offset:6144
	ds_read_b128 v[228:231], v155 offset:7168
	global_load_lds_dwordx4 v142, s[26:27]
	s_add_i32 m0, s3, 0xe000
	s_nop 0
	global_load_lds_dwordx4 v144, s[26:27]
	s_waitcnt vmcnt(8)
	s_waitcnt lgkmcnt(0)
	s_setprio 1
	s_barrier
	v_mfma_f32_16x16x32_bf16 v[126:129], v[166:169], v[198:201], 0
	v_mfma_f32_16x16x32_bf16 v[122:125], v[174:177], v[198:201], 0
	v_mfma_f32_16x16x32_bf16 v[110:113], v[166:169], v[206:209], 0
	v_mfma_f32_16x16x32_bf16 v[106:109], v[174:177], v[206:209], 0
	v_mfma_f32_16x16x32_bf16 v[94:97], v[166:169], v[214:217], 0
	v_mfma_f32_16x16x32_bf16 v[90:93], v[174:177], v[214:217], 0
	v_mfma_f32_16x16x32_bf16 v[78:81], v[166:169], v[224:227], 0
	v_mfma_f32_16x16x32_bf16 v[74:77], v[174:177], v[224:227], 0
	v_mfma_f32_16x16x32_bf16 v[126:129], v[170:173], v[202:205], v[126:129]
	v_mfma_f32_16x16x32_bf16 v[122:125], v[178:181], v[202:205], v[122:125]
	v_mfma_f32_16x16x32_bf16 v[110:113], v[170:173], v[210:213], v[110:113]
	v_mfma_f32_16x16x32_bf16 v[106:109], v[178:181], v[210:213], v[106:109]
	v_mfma_f32_16x16x32_bf16 v[94:97], v[170:173], v[220:223], v[94:97]
	v_mfma_f32_16x16x32_bf16 v[90:93], v[178:181], v[220:223], v[90:93]
	v_mfma_f32_16x16x32_bf16 v[78:81], v[170:173], v[228:231], v[78:81]
	v_mfma_f32_16x16x32_bf16 v[74:77], v[178:181], v[228:231], v[74:77]
	s_setprio 0
	s_setprio 1
	v_mfma_f32_16x16x32_bf16 v[118:121], v[182:185], v[198:201], 0
	v_mfma_f32_16x16x32_bf16 v[114:117], v[190:193], v[198:201], 0
	v_mfma_f32_16x16x32_bf16 v[102:105], v[182:185], v[206:209], 0
	v_mfma_f32_16x16x32_bf16 v[98:101], v[190:193], v[206:209], 0
	v_mfma_f32_16x16x32_bf16 v[86:89], v[182:185], v[214:217], 0
	v_mfma_f32_16x16x32_bf16 v[82:85], v[190:193], v[214:217], 0
	v_mfma_f32_16x16x32_bf16 v[70:73], v[182:185], v[224:227], 0
	v_mfma_f32_16x16x32_bf16 v[66:69], v[190:193], v[224:227], 0
	v_mfma_f32_16x16x32_bf16 v[118:121], v[186:189], v[202:205], v[118:121]
	v_mfma_f32_16x16x32_bf16 v[114:117], v[194:197], v[202:205], v[114:117]
	v_mfma_f32_16x16x32_bf16 v[102:105], v[186:189], v[210:213], v[102:105]
	v_mfma_f32_16x16x32_bf16 v[98:101], v[194:197], v[210:213], v[98:101]
	v_mfma_f32_16x16x32_bf16 v[86:89], v[186:189], v[220:223], v[86:89]
	v_mfma_f32_16x16x32_bf16 v[82:85], v[194:197], v[220:223], v[82:85]
	v_mfma_f32_16x16x32_bf16 v[70:73], v[186:189], v[228:231], v[70:73]
	v_mfma_f32_16x16x32_bf16 v[66:69], v[194:197], v[228:231], v[66:69]
	s_barrier
	s_setprio 0
	s_add_i32 s66, s8, s1
	s_mov_b32 m0, s66
	ds_read_b128 v[198:201], v155 offset:16384
	ds_read_b128 v[202:205], v155 offset:17408
	ds_read_b128 v[206:209], v155 offset:18432
	ds_read_b128 v[210:213], v155 offset:19456
	ds_read_b128 v[214:217], v155 offset:20480
	ds_read_b128 v[220:223], v155 offset:21504
	ds_read_b128 v[224:227], v155 offset:22528
	ds_read_b128 v[228:231], v155 offset:23552
	global_load_lds_dwordx4 v132, s[36:37]
	s_add_i32 m0, s66, 0x2000
	s_add_u32 s66, s36, 0x1000
	s_addc_u32 s67, s37, 0
	s_add_i32 s68, s52, s1
	global_load_lds_dwordx4 v136, s[36:37]
	s_mov_b32 m0, s68
	s_nop 0
	global_load_lds_dwordx4 v132, s[66:67]
	s_add_i32 m0, s68, 0x2000
	s_nop 0
	global_load_lds_dwordx4 v136, s[66:67]
	s_mov_b32 m0, s3
	s_nop 0
	global_load_lds_dwordx4 v130, s[42:43]
	s_mov_b32 m0, s44
	s_nop 0
	global_load_lds_dwordx4 v134, s[42:43]
	s_waitcnt vmcnt(8)
	s_waitcnt lgkmcnt(0)
	s_setprio 1
	s_barrier
; #define PG8_STAGE(bufoff, gbase, voff) do { _Pragma("unroll") for (int _i = 0; _i < 2; ++_i) \
;         __builtin_amdgcn_global_load_lds((const unsigned*)((const char*)(gbase) + (voff)[_i]), (PG8_LAS unsigned*)(lds + (bufoff) + ldsw + _i * 8192), 16, 0, 0); } while (0)
; #define PG8_LDA(dst, b, h) do { _Pragma("unroll") for (int m = 0; m < 4; ++m) _Pragma("unroll") for (int k = 0; k < 2; ++k) dst[m][k] = *(const PG8_LAS bf16x8*)(lds + PG8_SA(b, h) + aoff + m * 2048 + k * 1024); } while (0)
; #define PG8_LDB(dst, b, h) do { _Pragma("unroll") for (int n = 0; n < 2; ++n) _Pragma("unroll") for (int k = 0; k < 2; ++k) dst[n][k] = *(const PG8_LAS bf16x8*)(lds + PG8_SB(b, h) + boff + n * 2048 + k * 1024); } while (0)
; #define PG8_MMA(ai, bj, At, Bt) do { __builtin_amdgcn_s_setprio(1); _Pragma("unroll") for (int m = 0; m < 4; ++m) _Pragma("unroll") for (int n = 0; n < 2; ++n) _Pragma("unroll") for (int k = 0; k < 2; ++k) \
;         acc[ai][bj][m][n] = __builtin_amdgcn_mfma_f32_16x16x32_bf16(Bt[n][k], At[m][k], acc[ai][bj][m][n], 0, 0, 0); __builtin_amdgcn_s_setprio(0); } while (0)
; #define PG8_WAIT_V(n) asm volatile("s_waitcnt vmcnt(" #n ")" ::: "memory")
; #define PG8_WAIT_L(n) asm volatile("s_waitcnt lgkmcnt(" #n ")" ::: "memory")
; #define PG8_BAR __builtin_amdgcn_s_barrier()
; #define PG8_SCHED __builtin_amdgcn_sched_barrier(0)
; template <class Epi, class Sched, bool ALIGN_EPI = false, bool SP2 = false>
; __device__ __forceinline__ void gemm_phase(PG8_LAS unsigned char* lds, const Gemm g, const Sched& S, const Epi& E) {
;     ...
;             PG8_WAIT_V(8); PG8_WAIT_L(0); PG8_BAR; PG8_MMA(1, 0, At, B0); PG8_MMA(1, 1, At, B1); PG8_BAR; PG8_SCHED;
;             PG8_LDB(B0, 1, 0); PG8_LDB(B1, 1, 1); PG8_SCHED; PG8_LDA(At, 1, 0); PG8_STAGE(PG8_SA(0, 1), a2 + hstep, voffA);
;             PG8_WAIT_V(8); PG8_WAIT_L(0); PG8_BAR; PG8_MMA(0, 0, At, B0); PG8_MMA(0, 1, At, B1); PG8_BAR; PG8_SCHED;
	v_mfma_f32_16x16x32_bf16 v[62:65], v[166:169], v[198:201], 0
	v_mfma_f32_16x16x32_bf16 v[58:61], v[174:177], v[198:201], 0
	v_mfma_f32_16x16x32_bf16 v[46:49], v[166:169], v[206:209], 0
	v_mfma_f32_16x16x32_bf16 v[42:45], v[174:177], v[206:209], 0
	v_mfma_f32_16x16x32_bf16 v[30:33], v[166:169], v[214:217], 0
	v_mfma_f32_16x16x32_bf16 v[26:29], v[174:177], v[214:217], 0
	v_mfma_f32_16x16x32_bf16 v[14:17], v[166:169], v[224:227], 0
	v_mfma_f32_16x16x32_bf16 v[10:13], v[174:177], v[224:227], 0
	v_mfma_f32_16x16x32_bf16 v[62:65], v[170:173], v[202:205], v[62:65]
	v_mfma_f32_16x16x32_bf16 v[58:61], v[178:181], v[202:205], v[58:61]
	v_mfma_f32_16x16x32_bf16 v[46:49], v[170:173], v[210:213], v[46:49]
	v_mfma_f32_16x16x32_bf16 v[42:45], v[178:181], v[210:213], v[42:45]
	v_mfma_f32_16x16x32_bf16 v[30:33], v[170:173], v[220:223], v[30:33]
	v_mfma_f32_16x16x32_bf16 v[26:29], v[178:181], v[220:223], v[26:29]
	v_mfma_f32_16x16x32_bf16 v[14:17], v[170:173], v[228:231], v[14:17]
	v_mfma_f32_16x16x32_bf16 v[10:13], v[178:181], v[228:231], v[10:13]
	s_setprio 0
	s_setprio 1
	v_mfma_f32_16x16x32_bf16 v[54:57], v[182:185], v[198:201], 0
	v_mfma_f32_16x16x32_bf16 v[50:53], v[190:193], v[198:201], 0
	v_mfma_f32_16x16x32_bf16 v[38:41], v[182:185], v[206:209], 0
	v_mfma_f32_16x16x32_bf16 v[34:37], v[190:193], v[206:209], 0
	v_mfma_f32_16x16x32_bf16 v[22:25], v[182:185], v[214:217], 0
	v_mfma_f32_16x16x32_bf16 v[18:21], v[190:193], v[214:217], 0
	v_mfma_f32_16x16x32_bf16 v[6:9], v[182:185], v[224:227], 0
	v_mfma_f32_16x16x32_bf16 v[2:5], v[190:193], v[224:227], 0
	v_mfma_f32_16x16x32_bf16 v[54:57], v[186:189], v[202:205], v[54:57]
	v_mfma_f32_16x16x32_bf16 v[50:53], v[194:197], v[202:205], v[50:53]
	v_mfma_f32_16x16x32_bf16 v[38:41], v[186:189], v[210:213], v[38:41]
	v_mfma_f32_16x16x32_bf16 v[34:37], v[194:197], v[210:213], v[34:37]
	v_mfma_f32_16x16x32_bf16 v[22:25], v[186:189], v[220:223], v[22:25]
	v_mfma_f32_16x16x32_bf16 v[18:21], v[194:197], v[220:223], v[18:21]
	v_mfma_f32_16x16x32_bf16 v[6:9], v[186:189], v[228:231], v[6:9]
	v_mfma_f32_16x16x32_bf16 v[2:5], v[194:197], v[228:231], v[2:5]
	s_barrier
	s_setprio 0
	s_add_i32 s66, 0, 0x18000
	v_add_u32_e32 v165, s66, v151
	s_add_i32 s67, 0, 0x1c000
	ds_read_b128 v[166:169], v165
	ds_read_b128 v[170:173], v165 offset:1024
	ds_read_b128 v[174:177], v165 offset:2048
	ds_read_b128 v[178:181], v165 offset:3072
	v_add_u32_e32 v165, s67, v151
	ds_read_b128 v[182:185], v165
	ds_read_b128 v[186:189], v165 offset:1024
	ds_read_b128 v[190:193], v165 offset:2048
	ds_read_b128 v[194:197], v165 offset:3072
	s_add_u32 s42, s42, 0x4000
	s_addc_u32 s43, s43, 0
	s_mov_b32 m0, s45
	ds_read_b128 v[198:201], v155 offset:32768
	ds_read_b128 v[202:205], v155 offset:33792
	ds_read_b128 v[206:209], v155 offset:34816
	ds_read_b128 v[210:213], v155 offset:35840
	ds_read_b128 v[214:217], v155 offset:36864
	ds_read_b128 v[220:223], v155 offset:37888
	ds_read_b128 v[224:227], v155 offset:38912
	ds_read_b128 v[228:231], v155 offset:39936
	global_load_lds_dwordx4 v130, s[42:43]
	s_mov_b32 m0, s46
	s_nop 0
	global_load_lds_dwordx4 v134, s[42:43]
	s_waitcnt vmcnt(8)
	s_waitcnt lgkmcnt(0)
	s_setprio 1
	s_barrier
	v_mfma_f32_16x16x32_bf16 v[126:129], v[166:169], v[198:201], v[126:129]
	v_mfma_f32_16x16x32_bf16 v[122:125], v[174:177], v[198:201], v[122:125]
	v_mfma_f32_16x16x32_bf16 v[110:113], v[166:169], v[206:209], v[110:113]
	v_mfma_f32_16x16x32_bf16 v[106:109], v[174:177], v[206:209], v[106:109]
	v_mfma_f32_16x16x32_bf16 v[94:97], v[166:169], v[214:217], v[94:97]
	v_mfma_f32_16x16x32_bf16 v[90:93], v[174:177], v[214:217], v[90:93]
	v_mfma_f32_16x16x32_bf16 v[78:81], v[166:169], v[224:227], v[78:81]
	v_mfma_f32_16x16x32_bf16 v[74:77], v[174:177], v[224:227], v[74:77]
	v_mfma_f32_16x16x32_bf16 v[126:129], v[170:173], v[202:205], v[126:129]
	v_mfma_f32_16x16x32_bf16 v[122:125], v[178:181], v[202:205], v[122:125]
	v_mfma_f32_16x16x32_bf16 v[110:113], v[170:173], v[210:213], v[110:113]
	v_mfma_f32_16x16x32_bf16 v[106:109], v[178:181], v[210:213], v[106:109]
	v_mfma_f32_16x16x32_bf16 v[94:97], v[170:173], v[220:223], v[94:97]
	v_mfma_f32_16x16x32_bf16 v[90:93], v[178:181], v[220:223], v[90:93]
	v_mfma_f32_16x16x32_bf16 v[78:81], v[170:173], v[228:231], v[78:81]
	v_mfma_f32_16x16x32_bf16 v[74:77], v[178:181], v[228:231], v[74:77]
	s_setprio 0
	s_setprio 1
	v_mfma_f32_16x16x32_bf16 v[118:121], v[182:185], v[198:201], v[118:121]
	v_mfma_f32_16x16x32_bf16 v[114:117], v[190:193], v[198:201], v[114:117]
	v_mfma_f32_16x16x32_bf16 v[102:105], v[182:185], v[206:209], v[102:105]
	v_mfma_f32_16x16x32_bf16 v[98:101], v[190:193], v[206:209], v[98:101]
	v_mfma_f32_16x16x32_bf16 v[86:89], v[182:185], v[214:217], v[86:89]
	v_mfma_f32_16x16x32_bf16 v[82:85], v[190:193], v[214:217], v[82:85]
	v_mfma_f32_16x16x32_bf16 v[70:73], v[182:185], v[224:227], v[70:73]
	v_mfma_f32_16x16x32_bf16 v[66:69], v[190:193], v[224:227], v[66:69]
	v_mfma_f32_16x16x32_bf16 v[118:121], v[186:189], v[202:205], v[118:121]
	v_mfma_f32_16x16x32_bf16 v[114:117], v[194:197], v[202:205], v[114:117]
	v_mfma_f32_16x16x32_bf16 v[102:105], v[186:189], v[210:213], v[102:105]
	v_mfma_f32_16x16x32_bf16 v[98:101], v[194:197], v[210:213], v[98:101]
	v_mfma_f32_16x16x32_bf16 v[86:89], v[186:189], v[220:223], v[86:89]
	v_mfma_f32_16x16x32_bf16 v[82:85], v[194:197], v[220:223], v[82:85]
	v_mfma_f32_16x16x32_bf16 v[70:73], v[186:189], v[228:231], v[70:73]
	v_mfma_f32_16x16x32_bf16 v[66:69], v[194:197], v[228:231], v[66:69]
	s_barrier
; #define PG8_STAGE(bufoff, gbase, voff) do { _Pragma("unroll") for (int _i = 0; _i < 2; ++_i) \
;         __builtin_amdgcn_global_load_lds((const unsigned*)((const char*)(gbase) + (voff)[_i]), (PG8_LAS unsigned*)(lds + (bufoff) + ldsw + _i * 8192), 16, 0, 0); } while (0)
; #define PG8_LDA(dst, b, h) do { _Pragma("unroll") for (int m = 0; m < 4; ++m) _Pragma("unroll") for (int k = 0; k < 2; ++k) dst[m][k] = *(const PG8_LAS bf16x8*)(lds + PG8_SA(b, h) + aoff + m * 2048 + k * 1024); } while (0)
; #define PG8_MMA(ai, bj, At, Bt) do { __builtin_amdgcn_s_setprio(1); _Pragma("unroll") for (int m = 0; m < 4; ++m) _Pragma("unroll") for (int n = 0; n < 2; ++n) _Pragma("unroll") for (int k = 0; k < 2; ++k) \
;         acc[ai][bj][m][n] = __builtin_amdgcn_mfma_f32_16x16x32_bf16(Bt[n][k], At[m][k], acc[ai][bj][m][n], 0, 0, 0); __builtin_amdgcn_s_setprio(0); } while (0)
; #define PG8_WAIT_V(n) asm volatile("s_waitcnt vmcnt(" #n ")" ::: "memory")
; #define PG8_WAIT_L(n) asm volatile("s_waitcnt lgkmcnt(" #n ")" ::: "memory")
; #define PG8_BAR __builtin_amdgcn_s_barrier()
; #define PG8_SCHED __builtin_amdgcn_sched_barrier(0)
; template <class Epi, class Sched, bool ALIGN_EPI = false, bool SP2 = false>
; __device__ __forceinline__ void gemm_phase(PG8_LAS unsigned char* lds, const Gemm g, const Sched& S, const Epi& E) {
;     ...
;             PG8_LDA(At, 1, 1); PG8_STAGE(PG8_SB(1, 0), b3, voffB); PG8_STAGE(PG8_SB(1, 1), b3 + hstepB, voffB); PG8_STAGE(PG8_SA(1, 0), a3, voffA);
;             PG8_WAIT_V(8); PG8_WAIT_L(0); PG8_BAR; PG8_MMA(1, 0, At, B0); PG8_MMA(1, 1, At, B1); PG8_BAR; PG8_SCHED;
	s_setprio 0
	s_add_u32 s42, s36, 0x8000
	s_addc_u32 s43, s37, 0
	s_add_i32 s66, s66, s1
	s_mov_b32 m0, s66
	ds_read_b128 v[198:201], v155 offset:49152
	ds_read_b128 v[202:205], v155 offset:50176
	ds_read_b128 v[206:209], v155 offset:51200
	ds_read_b128 v[210:213], v155 offset:52224
	ds_read_b128 v[214:217], v155 offset:53248
	ds_read_b128 v[220:223], v155 offset:54272
	ds_read_b128 v[224:227], v155 offset:55296
	ds_read_b128 v[228:231], v155 offset:56320
	global_load_lds_dwordx4 v132, s[42:43]
	s_add_i32 m0, s66, 0x2000
	s_add_u32 s36, s36, 0x9000
	v_lshl_add_u64 v[232:233], s[42:43], 0, v[136:137]
	s_addc_u32 s37, s37, 0
	s_add_i32 s42, s67, s1
	global_load_lds_dwordx4 v[232:233], off
	s_mov_b32 m0, s42
	s_nop 0
	global_load_lds_dwordx4 v132, s[36:37]
	s_add_i32 m0, s42, 0x2000
	s_nop 0
	global_load_lds_dwordx4 v136, s[36:37]
	s_mov_b32 m0, s49
	s_nop 0
	global_load_lds_dwordx4 v130, s[28:29]
	s_mov_b32 m0, s50
	s_nop 0
	global_load_lds_dwordx4 v134, s[28:29]
	s_waitcnt vmcnt(8)
	s_waitcnt lgkmcnt(0)
	s_setprio 1
	s_barrier
	v_mfma_f32_16x16x32_bf16 v[62:65], v[166:169], v[198:201], v[62:65]
	v_mfma_f32_16x16x32_bf16 v[58:61], v[174:177], v[198:201], v[58:61]
	v_mfma_f32_16x16x32_bf16 v[46:49], v[166:169], v[206:209], v[46:49]
	v_mfma_f32_16x16x32_bf16 v[42:45], v[174:177], v[206:209], v[42:45]
	v_mfma_f32_16x16x32_bf16 v[30:33], v[166:169], v[214:217], v[30:33]
	v_mfma_f32_16x16x32_bf16 v[26:29], v[174:177], v[214:217], v[26:29]
	v_mfma_f32_16x16x32_bf16 v[14:17], v[166:169], v[224:227], v[14:17]
	v_mfma_f32_16x16x32_bf16 v[10:13], v[174:177], v[224:227], v[10:13]
	v_mfma_f32_16x16x32_bf16 v[62:65], v[170:173], v[202:205], v[62:65]
	v_mfma_f32_16x16x32_bf16 v[58:61], v[178:181], v[202:205], v[58:61]
	v_mfma_f32_16x16x32_bf16 v[46:49], v[170:173], v[210:213], v[46:49]
	v_mfma_f32_16x16x32_bf16 v[42:45], v[178:181], v[210:213], v[42:45]
	v_mfma_f32_16x16x32_bf16 v[30:33], v[170:173], v[220:223], v[30:33]
	v_mfma_f32_16x16x32_bf16 v[26:29], v[178:181], v[220:223], v[26:29]
	v_mfma_f32_16x16x32_bf16 v[14:17], v[170:173], v[228:231], v[14:17]
	v_mfma_f32_16x16x32_bf16 v[10:13], v[178:181], v[228:231], v[10:13]
	s_setprio 0
	s_setprio 1
	v_mfma_f32_16x16x32_bf16 v[54:57], v[182:185], v[198:201], v[54:57]
	v_mfma_f32_16x16x32_bf16 v[50:53], v[190:193], v[198:201], v[50:53]
	v_mfma_f32_16x16x32_bf16 v[38:41], v[182:185], v[206:209], v[38:41]
	v_mfma_f32_16x16x32_bf16 v[34:37], v[190:193], v[206:209], v[34:37]
	v_mfma_f32_16x16x32_bf16 v[22:25], v[182:185], v[214:217], v[22:25]
	v_mfma_f32_16x16x32_bf16 v[18:21], v[190:193], v[214:217], v[18:21]
	v_mfma_f32_16x16x32_bf16 v[6:9], v[182:185], v[224:227], v[6:9]
	v_mfma_f32_16x16x32_bf16 v[2:5], v[190:193], v[224:227], v[2:5]
	v_mfma_f32_16x16x32_bf16 v[54:57], v[186:189], v[202:205], v[54:57]
	v_mfma_f32_16x16x32_bf16 v[50:53], v[194:197], v[202:205], v[50:53]
	v_mfma_f32_16x16x32_bf16 v[38:41], v[186:189], v[210:213], v[38:41]
	v_mfma_f32_16x16x32_bf16 v[34:37], v[194:197], v[210:213], v[34:37]
	v_mfma_f32_16x16x32_bf16 v[22:25], v[186:189], v[220:223], v[22:25]
	v_mfma_f32_16x16x32_bf16 v[18:21], v[194:197], v[220:223], v[18:21]
	v_mfma_f32_16x16x32_bf16 v[6:9], v[186:189], v[228:231], v[6:9]
	v_mfma_f32_16x16x32_bf16 v[2:5], v[194:197], v[228:231], v[2:5]
	s_barrier
	s_setprio 0
	s_add_i32 s59, s59, 2
	s_add_u32 s26, s26, 0x10000
	s_addc_u32 s27, s27, 0
	s_add_u32 s57, s57, 0x10000
	s_addc_u32 s58, s58, 0

; #define PG8_STAGE(bufoff, gbase, voff) do { _Pragma("unroll") for (int _i = 0; _i < 2; ++_i) \
;         __builtin_amdgcn_global_load_lds((const unsigned*)((const char*)(gbase) + (voff)[_i]), (PG8_LAS unsigned*)(lds + (bufoff) + ldsw + _i * 8192), 16, 0, 0); } while (0)
; #define PG8_LDA(dst, b, h) do { _Pragma("unroll") for (int m = 0; m < 4; ++m) _Pragma("unroll") for (int k = 0; k < 2; ++k) dst[m][k] = *(const PG8_LAS bf16x8*)(lds + PG8_SA(b, h) + aoff + m * 2048 + k * 1024); } while (0)
; #define PG8_LDB(dst, b, h) do { _Pragma("unroll") for (int n = 0; n < 2; ++n) _Pragma("unroll") for (int k = 0; k < 2; ++k) dst[n][k] = *(const PG8_LAS bf16x8*)(lds + PG8_SB(b, h) + boff + n * 2048 + k * 1024); } while (0)
; #define PG8_MMA(ai, bj, At, Bt) do { __builtin_amdgcn_s_setprio(1); _Pragma("unroll") for (int m = 0; m < 4; ++m) _Pragma("unroll") for (int n = 0; n < 2; ++n) _Pragma("unroll") for (int k = 0; k < 2; ++k) \
;         acc[ai][bj][m][n] = __builtin_amdgcn_mfma_f32_16x16x32_bf16(Bt[n][k], At[m][k], acc[ai][bj][m][n], 0, 0, 0); __builtin_amdgcn_s_setprio(0); } while (0)
; template <class Epi, class Sched, bool ALIGN_EPI = false, bool SP2 = false>
; __device__ __forceinline__ void gemm_phase(PG8_LAS unsigned char* lds, const Gemm g, const Sched& S, const Epi& E) {
;     ...
;         const char* nA = has_next ? (const char*)g.A + (size_t)nxt.pm * tstep : cA; const char* nB = has_next ? (const char*)g.Bt + (size_t)nxt.pn * tstep : cB;
;         for (int t = 0; t < nt; t += 2) {
;             if constexpr (Epi::HAS_MID) { if (t == (nt >> 1)) E.mid(acc, cur, wr, wc, fr, fq); }
;             const bool last = (t == nt - 2);
;             const char* a1 = cA + (size_t)(t + 1) * kstep;
;             const char* a2 = last ? nA : cA + (size_t)(t + 2) * kstep; const char* b2 = last ? nB : cB + (size_t)(t + 2) * kstep;
;             const char* a3 = a2 + kstep; const char* b3 = b2 + kstep;
;             if (last && has_next) S.a_ready(nxt);
;             if constexpr (SP2) {
;             PG8_LDB(B0, 0, 0); PG8_LDB(B1, 0, 1); PG8_SCHED; PG8_LDA(At, 0, 0); PG8_STAGE(PG8_SA(1, 1), a1 + hstep, voffA);
;             PG8_WAIT_V(8); PG8_WAIT_L(0); PG8_BAR; PG8_MMA(0, 0, At, B0); PG8_MMA(0, 1, At, B1); PG8_BAR; PG8_SCHED;
;             PG8_LDA(At, 0, 1); PG8_STAGE(PG8_SB(0, 0), b2, voffB); PG8_STAGE(PG8_SB(0, 1), b2 + hstepB, voffB); PG8_STAGE(PG8_SA(0, 0), a2, voffA);
.LBB0_681:
	s_ashr_i32 s23, s22, 31
	s_lshl_b64 s[24:25], s[22:23], 21
	s_add_u32 s24, s38, s24
	s_addc_u32 s25, s39, s25
	s_and_b64 s[26:27], s[4:5], exec
	s_cselect_b32 s9, s25, s37
	s_cselect_b32 s23, s24, s36
	s_ashr_i32 s21, s20, 31
	s_lshl_b64 s[26:27], s[20:21], 21
	s_add_u32 s26, s60, s26
	s_addc_u32 s27, s61, s27
	s_and_b64 s[44:45], s[4:5], exec
	s_cselect_b32 s21, s27, s43
	s_cselect_b32 s29, s26, s42
	s_add_u32 s36, s36, 0xc000
	s_addc_u32 s37, s37, 0
	s_add_u32 s52, s42, 0x10000
	s_addc_u32 s53, s43, 0
	s_mov_b32 s54, -2
	s_waitcnt lgkmcnt(0)
	ds_read_b128 v[98:101], v215
	ds_read_b128 v[102:105], v215 offset:1024
	ds_read_b128 v[122:125], v215 offset:2048
	ds_read_b128 v[126:129], v215 offset:3072
	ds_read_b128 v[146:149], v216
	ds_read_b128 v[150:153], v216 offset:1024
	ds_read_b128 v[154:157], v216 offset:2048
	ds_read_b128 v[158:161], v216 offset:3072
	s_add_u32 s42, s36, 0x4000
	s_addc_u32 s43, s37, 0
	s_cmp_eq_u32 s54, 60
	s_cselect_b32 s46, s23, s42
	s_cselect_b32 s47, s9, s43
	s_cselect_b32 s44, s29, s52
	s_cselect_b32 s45, s21, s53
	s_add_u32 s42, s46, 0x8000
	s_addc_u32 s43, s47, 0
	s_add_i32 m0, s1, 0xc000
	ds_read_b128 v[162:165], v217
	ds_read_b128 v[166:169], v217 offset:1024
	ds_read_b128 v[170:173], v217 offset:2048
	ds_read_b128 v[174:177], v217 offset:3072
	ds_read_b128 v[178:181], v217 offset:4096
	ds_read_b128 v[182:185], v217 offset:5120
	ds_read_b128 v[222:225], v217 offset:6144
	ds_read_b128 v[226:229], v217 offset:7168
	global_load_lds_dwordx4 v198, s[36:37]
	s_add_i32 m0, s1, 0xe000
	s_nop 0
	global_load_lds_dwordx4 v200, s[36:37]
	s_waitcnt vmcnt(8)
	s_waitcnt lgkmcnt(0)
	s_setprio 1
	s_barrier
	v_mfma_f32_16x16x32_bf16 v[142:145], v[98:101], v[162:165], 0
	v_mfma_f32_16x16x32_bf16 v[138:141], v[122:125], v[162:165], 0
	v_mfma_f32_16x16x32_bf16 v[118:121], v[98:101], v[170:173], 0
	v_mfma_f32_16x16x32_bf16 v[114:117], v[122:125], v[170:173], 0
	v_mfma_f32_16x16x32_bf16 v[94:97], v[98:101], v[178:181], 0
	v_mfma_f32_16x16x32_bf16 v[90:93], v[122:125], v[178:181], 0
	v_mfma_f32_16x16x32_bf16 v[78:81], v[98:101], v[222:225], 0
	v_mfma_f32_16x16x32_bf16 v[74:77], v[122:125], v[222:225], 0
	v_mfma_f32_16x16x32_bf16 v[142:145], v[102:105], v[166:169], v[142:145]
	v_mfma_f32_16x16x32_bf16 v[138:141], v[126:129], v[166:169], v[138:141]
	v_mfma_f32_16x16x32_bf16 v[118:121], v[102:105], v[174:177], v[118:121]
	v_mfma_f32_16x16x32_bf16 v[114:117], v[126:129], v[174:177], v[114:117]
	v_mfma_f32_16x16x32_bf16 v[94:97], v[102:105], v[182:185], v[94:97]
	v_mfma_f32_16x16x32_bf16 v[90:93], v[126:129], v[182:185], v[90:93]
	v_mfma_f32_16x16x32_bf16 v[78:81], v[102:105], v[226:229], v[78:81]
	v_mfma_f32_16x16x32_bf16 v[74:77], v[126:129], v[226:229], v[74:77]
	s_setprio 0
	s_setprio 1
	v_mfma_f32_16x16x32_bf16 v[134:137], v[146:149], v[162:165], 0
	v_mfma_f32_16x16x32_bf16 v[130:133], v[154:157], v[162:165], 0
	v_mfma_f32_16x16x32_bf16 v[110:113], v[146:149], v[170:173], 0
	v_mfma_f32_16x16x32_bf16 v[106:109], v[154:157], v[170:173], 0
	v_mfma_f32_16x16x32_bf16 v[86:89], v[146:149], v[178:181], 0
	v_mfma_f32_16x16x32_bf16 v[82:85], v[154:157], v[178:181], 0
	v_mfma_f32_16x16x32_bf16 v[70:73], v[146:149], v[222:225], 0
	v_mfma_f32_16x16x32_bf16 v[66:69], v[154:157], v[222:225], 0
	v_mfma_f32_16x16x32_bf16 v[134:137], v[150:153], v[166:169], v[134:137]
	v_mfma_f32_16x16x32_bf16 v[130:133], v[158:161], v[166:169], v[130:133]
	v_mfma_f32_16x16x32_bf16 v[110:113], v[150:153], v[174:177], v[110:113]
	v_mfma_f32_16x16x32_bf16 v[106:109], v[158:161], v[174:177], v[106:109]
	v_mfma_f32_16x16x32_bf16 v[86:89], v[150:153], v[182:185], v[86:89]
	v_mfma_f32_16x16x32_bf16 v[82:85], v[158:161], v[182:185], v[82:85]
	v_mfma_f32_16x16x32_bf16 v[70:73], v[150:153], v[226:229], v[70:73]
	v_mfma_f32_16x16x32_bf16 v[66:69], v[158:161], v[226:229], v[66:69]
	s_barrier
	s_setprio 0
	s_add_i32 s55, s59, s0
	s_mov_b32 m0, s55
	ds_read_b128 v[162:165], v217 offset:16384
	ds_read_b128 v[166:169], v217 offset:17408
	ds_read_b128 v[170:173], v217 offset:18432
	ds_read_b128 v[174:177], v217 offset:19456
	ds_read_b128 v[178:181], v217 offset:20480
	ds_read_b128 v[182:185], v217 offset:21504
	ds_read_b128 v[222:225], v217 offset:22528
	ds_read_b128 v[226:229], v217 offset:23552
	global_load_lds_dwordx4 v188, s[44:45]
	s_add_i32 m0, s55, 0x2000
	s_add_u32 s68, s44, 0x1000
	s_addc_u32 s69, s45, 0
	s_add_i32 s55, s64, s0
	global_load_lds_dwordx4 v192, s[44:45]
	s_mov_b32 m0, s55
	s_nop 0
	global_load_lds_dwordx4 v188, s[68:69]
	s_add_i32 m0, s55, 0x2000
	s_nop 0
	global_load_lds_dwordx4 v192, s[68:69]
	s_mov_b32 m0, s1
	s_nop 0
	global_load_lds_dwordx4 v186, s[46:47]
	s_mov_b32 m0, s3
	s_nop 0
	global_load_lds_dwordx4 v190, s[46:47]
	s_waitcnt vmcnt(8)
	s_waitcnt lgkmcnt(0)
	s_setprio 1
	s_barrier
; #define PG8_STAGE(bufoff, gbase, voff) do { _Pragma("unroll") for (int _i = 0; _i < 2; ++_i) \
;         __builtin_amdgcn_global_load_lds((const unsigned*)((const char*)(gbase) + (voff)[_i]), (PG8_LAS unsigned*)(lds + (bufoff) + ldsw + _i * 8192), 16, 0, 0); } while (0)
; #define PG8_LDA(dst, b, h) do { _Pragma("unroll") for (int m = 0; m < 4; ++m) _Pragma("unroll") for (int k = 0; k < 2; ++k) dst[m][k] = *(const PG8_LAS bf16x8*)(lds + PG8_SA(b, h) + aoff + m * 2048 + k * 1024); } while (0)
; #define PG8_LDB(dst, b, h) do { _Pragma("unroll") for (int n = 0; n < 2; ++n) _Pragma("unroll") for (int k = 0; k < 2; ++k) dst[n][k] = *(const PG8_LAS bf16x8*)(lds + PG8_SB(b, h) + boff + n * 2048 + k * 1024); } while (0)
; #define PG8_MMA(ai, bj, At, Bt) do { __builtin_amdgcn_s_setprio(1); _Pragma("unroll") for (int m = 0; m < 4; ++m) _Pragma("unroll") for (int n = 0; n < 2; ++n) _Pragma("unroll") for (int k = 0; k < 2; ++k) \
;         acc[ai][bj][m][n] = __builtin_amdgcn_mfma_f32_16x16x32_bf16(Bt[n][k], At[m][k], acc[ai][bj][m][n], 0, 0, 0); __builtin_amdgcn_s_setprio(0); } while (0)
; #define PG8_WAIT_V(n) asm volatile("s_waitcnt vmcnt(" #n ")" ::: "memory")
; #define PG8_WAIT_L(n) asm volatile("s_waitcnt lgkmcnt(" #n ")" ::: "memory")
; #define PG8_BAR __builtin_amdgcn_s_barrier()
; #define PG8_SCHED __builtin_amdgcn_sched_barrier(0)
; template <class Epi, class Sched, bool ALIGN_EPI = false, bool SP2 = false>
; __device__ __forceinline__ void gemm_phase(PG8_LAS unsigned char* lds, const Gemm g, const Sched& S, const Epi& E) {
;     ...
;             PG8_WAIT_V(8); PG8_WAIT_L(0); PG8_BAR; PG8_MMA(1, 0, At, B0); PG8_MMA(1, 1, At, B1); PG8_BAR; PG8_SCHED;
;             PG8_LDB(B0, 1, 0); PG8_LDB(B1, 1, 1); PG8_SCHED; PG8_LDA(At, 1, 0); PG8_STAGE(PG8_SA(0, 1), a2 + hstep, voffA);
;             PG8_WAIT_V(8); PG8_WAIT_L(0); PG8_BAR; PG8_MMA(0, 0, At, B0); PG8_MMA(0, 1, At, B1); PG8_BAR; PG8_SCHED;
	v_mfma_f32_16x16x32_bf16 v[62:65], v[98:101], v[162:165], 0
	v_mfma_f32_16x16x32_bf16 v[58:61], v[122:125], v[162:165], 0
	v_mfma_f32_16x16x32_bf16 v[46:49], v[98:101], v[170:173], 0
	v_mfma_f32_16x16x32_bf16 v[42:45], v[122:125], v[170:173], 0
	v_mfma_f32_16x16x32_bf16 v[30:33], v[98:101], v[178:181], 0
	v_mfma_f32_16x16x32_bf16 v[26:29], v[122:125], v[178:181], 0
	v_mfma_f32_16x16x32_bf16 v[14:17], v[98:101], v[222:225], 0
	v_mfma_f32_16x16x32_bf16 v[10:13], v[122:125], v[222:225], 0
	v_mfma_f32_16x16x32_bf16 v[62:65], v[102:105], v[166:169], v[62:65]
	v_mfma_f32_16x16x32_bf16 v[58:61], v[126:129], v[166:169], v[58:61]
	v_mfma_f32_16x16x32_bf16 v[46:49], v[102:105], v[174:177], v[46:49]
	v_mfma_f32_16x16x32_bf16 v[42:45], v[126:129], v[174:177], v[42:45]
	v_mfma_f32_16x16x32_bf16 v[30:33], v[102:105], v[182:185], v[30:33]
	v_mfma_f32_16x16x32_bf16 v[26:29], v[126:129], v[182:185], v[26:29]
	v_mfma_f32_16x16x32_bf16 v[14:17], v[102:105], v[226:229], v[14:17]
	v_mfma_f32_16x16x32_bf16 v[10:13], v[126:129], v[226:229], v[10:13]
	s_setprio 0
	s_setprio 1
	v_mfma_f32_16x16x32_bf16 v[54:57], v[146:149], v[162:165], 0
	v_mfma_f32_16x16x32_bf16 v[50:53], v[154:157], v[162:165], 0
	v_mfma_f32_16x16x32_bf16 v[38:41], v[146:149], v[170:173], 0
	v_mfma_f32_16x16x32_bf16 v[34:37], v[154:157], v[170:173], 0
	v_mfma_f32_16x16x32_bf16 v[22:25], v[146:149], v[178:181], 0
	v_mfma_f32_16x16x32_bf16 v[18:21], v[154:157], v[178:181], 0
	v_mfma_f32_16x16x32_bf16 v[6:9], v[146:149], v[222:225], 0
	v_mfma_f32_16x16x32_bf16 v[2:5], v[154:157], v[222:225], 0
	v_mfma_f32_16x16x32_bf16 v[54:57], v[150:153], v[166:169], v[54:57]
	v_mfma_f32_16x16x32_bf16 v[50:53], v[158:161], v[166:169], v[50:53]
	v_mfma_f32_16x16x32_bf16 v[38:41], v[150:153], v[174:177], v[38:41]
	v_mfma_f32_16x16x32_bf16 v[34:37], v[158:161], v[174:177], v[34:37]
	v_mfma_f32_16x16x32_bf16 v[22:25], v[150:153], v[182:185], v[22:25]
	v_mfma_f32_16x16x32_bf16 v[18:21], v[158:161], v[182:185], v[18:21]
	v_mfma_f32_16x16x32_bf16 v[6:9], v[150:153], v[226:229], v[6:9]
	v_mfma_f32_16x16x32_bf16 v[2:5], v[158:161], v[226:229], v[2:5]
	s_barrier
	s_setprio 0
	s_add_i32 s55, 0, 0x18000
	s_add_i32 s67, 0, 0x1c000
	v_add_u32_e32 v126, s55, v214
	v_add_u32_e32 v158, s67, v214
	ds_read_b128 v[98:101], v126
	ds_read_b128 v[102:105], v126 offset:1024
	ds_read_b128 v[122:125], v126 offset:2048
	ds_read_b128 v[126:129], v126 offset:3072
	ds_read_b128 v[146:149], v158
	ds_read_b128 v[150:153], v158 offset:1024
	ds_read_b128 v[154:157], v158 offset:2048
	ds_read_b128 v[158:161], v158 offset:3072
	s_add_u32 s46, s46, 0x4000
	s_addc_u32 s47, s47, 0
	s_mov_b32 m0, s48
	ds_read_b128 v[162:165], v217 offset:32768
	ds_read_b128 v[166:169], v217 offset:33792
	ds_read_b128 v[170:173], v217 offset:34816
	ds_read_b128 v[174:177], v217 offset:35840
	ds_read_b128 v[178:181], v217 offset:36864
	ds_read_b128 v[182:185], v217 offset:37888
	ds_read_b128 v[222:225], v217 offset:38912
	ds_read_b128 v[226:229], v217 offset:39936
	global_load_lds_dwordx4 v186, s[46:47]
	s_mov_b32 m0, s49
	s_nop 0
	global_load_lds_dwordx4 v190, s[46:47]
	s_waitcnt vmcnt(8)
	s_waitcnt lgkmcnt(0)
	s_setprio 1
	s_barrier
	v_mfma_f32_16x16x32_bf16 v[142:145], v[98:101], v[162:165], v[142:145]
	v_mfma_f32_16x16x32_bf16 v[138:141], v[122:125], v[162:165], v[138:141]
	v_mfma_f32_16x16x32_bf16 v[118:121], v[98:101], v[170:173], v[118:121]
	v_mfma_f32_16x16x32_bf16 v[114:117], v[122:125], v[170:173], v[114:117]
	v_mfma_f32_16x16x32_bf16 v[94:97], v[98:101], v[178:181], v[94:97]
	v_mfma_f32_16x16x32_bf16 v[90:93], v[122:125], v[178:181], v[90:93]
	v_mfma_f32_16x16x32_bf16 v[78:81], v[98:101], v[222:225], v[78:81]
	v_mfma_f32_16x16x32_bf16 v[74:77], v[122:125], v[222:225], v[74:77]
	v_mfma_f32_16x16x32_bf16 v[142:145], v[102:105], v[166:169], v[142:145]
	v_mfma_f32_16x16x32_bf16 v[138:141], v[126:129], v[166:169], v[138:141]
	v_mfma_f32_16x16x32_bf16 v[118:121], v[102:105], v[174:177], v[118:121]
	v_mfma_f32_16x16x32_bf16 v[114:117], v[126:129], v[174:177], v[114:117]
	v_mfma_f32_16x16x32_bf16 v[94:97], v[102:105], v[182:185], v[94:97]
	v_mfma_f32_16x16x32_bf16 v[90:93], v[126:129], v[182:185], v[90:93]
	v_mfma_f32_16x16x32_bf16 v[78:81], v[102:105], v[226:229], v[78:81]
	v_mfma_f32_16x16x32_bf16 v[74:77], v[126:129], v[226:229], v[74:77]
	s_setprio 0
	s_setprio 1
	v_mfma_f32_16x16x32_bf16 v[134:137], v[146:149], v[162:165], v[134:137]
	v_mfma_f32_16x16x32_bf16 v[130:133], v[154:157], v[162:165], v[130:133]
	v_mfma_f32_16x16x32_bf16 v[110:113], v[146:149], v[170:173], v[110:113]
	v_mfma_f32_16x16x32_bf16 v[106:109], v[154:157], v[170:173], v[106:109]
	v_mfma_f32_16x16x32_bf16 v[86:89], v[146:149], v[178:181], v[86:89]
	v_mfma_f32_16x16x32_bf16 v[82:85], v[154:157], v[178:181], v[82:85]
	v_mfma_f32_16x16x32_bf16 v[70:73], v[146:149], v[222:225], v[70:73]
	v_mfma_f32_16x16x32_bf16 v[66:69], v[154:157], v[222:225], v[66:69]
	v_mfma_f32_16x16x32_bf16 v[134:137], v[150:153], v[166:169], v[134:137]
	v_mfma_f32_16x16x32_bf16 v[130:133], v[158:161], v[166:169], v[130:133]
	v_mfma_f32_16x16x32_bf16 v[110:113], v[150:153], v[174:177], v[110:113]
	v_mfma_f32_16x16x32_bf16 v[106:109], v[158:161], v[174:177], v[106:109]
	v_mfma_f32_16x16x32_bf16 v[86:89], v[150:153], v[182:185], v[86:89]
	v_mfma_f32_16x16x32_bf16 v[82:85], v[158:161], v[182:185], v[82:85]
	v_mfma_f32_16x16x32_bf16 v[70:73], v[150:153], v[226:229], v[70:73]
	v_mfma_f32_16x16x32_bf16 v[66:69], v[158:161], v[226:229], v[66:69]
	s_barrier
; #define PG8_STAGE(bufoff, gbase, voff) do { _Pragma("unroll") for (int _i = 0; _i < 2; ++_i) \
;         __builtin_amdgcn_global_load_lds((const unsigned*)((const char*)(gbase) + (voff)[_i]), (PG8_LAS unsigned*)(lds + (bufoff) + ldsw + _i * 8192), 16, 0, 0); } while (0)
; #define PG8_LDA(dst, b, h) do { _Pragma("unroll") for (int m = 0; m < 4; ++m) _Pragma("unroll") for (int k = 0; k < 2; ++k) dst[m][k] = *(const PG8_LAS bf16x8*)(lds + PG8_SA(b, h) + aoff + m * 2048 + k * 1024); } while (0)
; #define PG8_MMA(ai, bj, At, Bt) do { __builtin_amdgcn_s_setprio(1); _Pragma("unroll") for (int m = 0; m < 4; ++m) _Pragma("unroll") for (int n = 0; n < 2; ++n) _Pragma("unroll") for (int k = 0; k < 2; ++k) \
;         acc[ai][bj][m][n] = __builtin_amdgcn_mfma_f32_16x16x32_bf16(Bt[n][k], At[m][k], acc[ai][bj][m][n], 0, 0, 0); __builtin_amdgcn_s_setprio(0); } while (0)
; #define PG8_WAIT_V(n) asm volatile("s_waitcnt vmcnt(" #n ")" ::: "memory")
; #define PG8_WAIT_L(n) asm volatile("s_waitcnt lgkmcnt(" #n ")" ::: "memory")
; #define PG8_BAR __builtin_amdgcn_s_barrier()
; #define PG8_SCHED __builtin_amdgcn_sched_barrier(0)
; template <class Epi, class Sched, bool ALIGN_EPI = false, bool SP2 = false>
; __device__ __forceinline__ void gemm_phase(PG8_LAS unsigned char* lds, const Gemm g, const Sched& S, const Epi& E) {
;     ...
;             PG8_LDA(At, 1, 1); PG8_STAGE(PG8_SB(1, 0), b3, voffB); PG8_STAGE(PG8_SB(1, 1), b3 + hstepB, voffB); PG8_STAGE(PG8_SA(1, 0), a3, voffA);
;             PG8_WAIT_V(8); PG8_WAIT_L(0); PG8_BAR; PG8_MMA(1, 0, At, B0); PG8_MMA(1, 1, At, B1); PG8_BAR; PG8_SCHED;
	s_setprio 0
	s_add_u32 s46, s44, 0x8000
	s_addc_u32 s47, s45, 0
	s_add_i32 s55, s55, s0
	s_mov_b32 m0, s55
	ds_read_b128 v[162:165], v217 offset:49152
	ds_read_b128 v[166:169], v217 offset:50176
	ds_read_b128 v[170:173], v217 offset:51200
	ds_read_b128 v[174:177], v217 offset:52224
	ds_read_b128 v[178:181], v217 offset:53248
	ds_read_b128 v[182:185], v217 offset:54272
	ds_read_b128 v[222:225], v217 offset:55296
	ds_read_b128 v[226:229], v217 offset:56320
	global_load_lds_dwordx4 v188, s[46:47]
	s_add_i32 m0, s55, 0x2000
	s_add_u32 s44, s44, 0x9000
	v_lshl_add_u64 v[230:231], s[46:47], 0, v[192:193]
	s_addc_u32 s45, s45, 0
	s_add_i32 s46, s67, s0
	global_load_lds_dwordx4 v[230:231], off
	s_mov_b32 m0, s46
	s_nop 0
	global_load_lds_dwordx4 v188, s[44:45]
	s_add_i32 m0, s46, 0x2000
	s_nop 0
	global_load_lds_dwordx4 v192, s[44:45]
	s_mov_b32 m0, s56
	s_nop 0
	global_load_lds_dwordx4 v186, s[42:43]
	s_mov_b32 m0, s57
	s_nop 0
	global_load_lds_dwordx4 v190, s[42:43]
	s_waitcnt vmcnt(8)
	s_waitcnt lgkmcnt(0)
	s_setprio 1
	s_barrier
	v_mfma_f32_16x16x32_bf16 v[62:65], v[98:101], v[162:165], v[62:65]
	v_mfma_f32_16x16x32_bf16 v[58:61], v[122:125], v[162:165], v[58:61]
	v_mfma_f32_16x16x32_bf16 v[46:49], v[98:101], v[170:173], v[46:49]
	v_mfma_f32_16x16x32_bf16 v[42:45], v[122:125], v[170:173], v[42:45]
	v_mfma_f32_16x16x32_bf16 v[30:33], v[98:101], v[178:181], v[30:33]
	v_mfma_f32_16x16x32_bf16 v[26:29], v[122:125], v[178:181], v[26:29]
	v_mfma_f32_16x16x32_bf16 v[14:17], v[98:101], v[222:225], v[14:17]
	v_mfma_f32_16x16x32_bf16 v[10:13], v[122:125], v[222:225], v[10:13]
	v_mfma_f32_16x16x32_bf16 v[62:65], v[102:105], v[166:169], v[62:65]
	v_mfma_f32_16x16x32_bf16 v[58:61], v[126:129], v[166:169], v[58:61]
	v_mfma_f32_16x16x32_bf16 v[46:49], v[102:105], v[174:177], v[46:49]
	v_mfma_f32_16x16x32_bf16 v[42:45], v[126:129], v[174:177], v[42:45]
	v_mfma_f32_16x16x32_bf16 v[30:33], v[102:105], v[182:185], v[30:33]
	v_mfma_f32_16x16x32_bf16 v[26:29], v[126:129], v[182:185], v[26:29]
	v_mfma_f32_16x16x32_bf16 v[14:17], v[102:105], v[226:229], v[14:17]
	v_mfma_f32_16x16x32_bf16 v[10:13], v[126:129], v[226:229], v[10:13]
	s_setprio 0
	s_setprio 1
	v_mfma_f32_16x16x32_bf16 v[54:57], v[146:149], v[162:165], v[54:57]
	v_mfma_f32_16x16x32_bf16 v[50:53], v[154:157], v[162:165], v[50:53]
	v_mfma_f32_16x16x32_bf16 v[38:41], v[146:149], v[170:173], v[38:41]
	v_mfma_f32_16x16x32_bf16 v[34:37], v[154:157], v[170:173], v[34:37]
	v_mfma_f32_16x16x32_bf16 v[22:25], v[146:149], v[178:181], v[22:25]
	v_mfma_f32_16x16x32_bf16 v[18:21], v[154:157], v[178:181], v[18:21]
	v_mfma_f32_16x16x32_bf16 v[6:9], v[146:149], v[222:225], v[6:9]
	v_mfma_f32_16x16x32_bf16 v[2:5], v[154:157], v[222:225], v[2:5]
	v_mfma_f32_16x16x32_bf16 v[54:57], v[150:153], v[166:169], v[54:57]
	v_mfma_f32_16x16x32_bf16 v[50:53], v[158:161], v[166:169], v[50:53]
	v_mfma_f32_16x16x32_bf16 v[38:41], v[150:153], v[174:177], v[38:41]
	v_mfma_f32_16x16x32_bf16 v[34:37], v[158:161], v[174:177], v[34:37]
	v_mfma_f32_16x16x32_bf16 v[22:25], v[150:153], v[182:185], v[22:25]
	v_mfma_f32_16x16x32_bf16 v[18:21], v[158:161], v[182:185], v[18:21]
	v_mfma_f32_16x16x32_bf16 v[6:9], v[150:153], v[226:229], v[6:9]
	v_mfma_f32_16x16x32_bf16 v[2:5], v[158:161], v[226:229], v[2:5]
	s_barrier
	s_setprio 0
	s_add_i32 s54, s54, 2
	s_add_u32 s36, s36, 0x10000
	s_addc_u32 s37, s37, 0
	s_add_u32 s52, s52, 0x10000
	s_addc_u32 s53, s53, 0
